# P0: odd workgroups run the implicit-filter MLP first and the weight/x conversion second (compute and memory sub-phases overlap across CUs); GEMM prologue issues all 14 staging loads before the first w
# speedup vs baseline: 1.0878x; 1.0069x over previous
; #define LAS __attribute__((address_space(3)))
; __global__ void __launch_bounds__(512, 2) hybrid_fwd(Args args) {
;     ...
;     unsigned char* ws = args.ws; unsigned char* ob = (unsigned char*)args.out;
;     float* SS0 = (float*)(ws + WS_CTL + CTL_SS0); float* SS1 = (float*)(ws + WS_CTL + CTL_SS1); float* SS2 = (float*)(ws + WS_CTL + CTL_SS2); float* F0 = (float*)(ws + WS_CTL + CTL_F0); unsigned* PCNT = (unsigned*)(ws + WS_CTL + CTL_CNT);
;     bf16* WIN = (bf16*)(ws + WS_WIN); bf16* WBA = (bf16*)(ws + WS_WBA); bf16* WBH = (bf16*)(ws + WS_WBH); bf16* WO = (bf16*)(ws + WS_WO); bf16* WGU = (bf16*)(ws + WS_WGU); bf16* WD = (bf16*)(ws + WS_WD);
;     bf16* XB = (bf16*)(ws + WS_XB); bf16* Qb = (bf16*)(ws + WS_Q); bf16* Kb = (bf16*)(ws + WS_K); bf16* VT = (bf16*)(ws + WS_VT);
;     bf16* FRP = (bf16*)(ws + WS_FRP); bf16* FRS = (bf16*)(ws + WS_FRS); bf16* M1 = (bf16*)(ws + WS_M1); bf16* Hb = (bf16*)(ws + WS_H);
;     bf16* HY = (bf16*)(ob + OUT_HY); bf16* UT = (bf16*)(ob + OUT_UT); bf16* M2 = (bf16*)(ob + OUT_M2);
;     const int lo = args.ph_lo, hi = args.ph_hi;
;     const int gw = F.bid * 8 + F.wave, NGW = F.G * 8;
;     volatile LAS unsigned* bar_st = (volatile LAS unsigned*)(F.lds + LDS_BYTES - 64);
;     if (F.tid < 2) bar_st[F.tid] = 0u;
;     __syncthreads();
;     XcdBarrier xbar = xcd_barrier_post((unsigned*)(ws + WS_CTL + CTL_BAR), bar_st);
;     if (lo > hi) { asm volatile("s_waitcnt vmcnt(0)" ::: "memory"); cg::this_grid().sync(); }
;     ...
;     DUP_BEGIN(0) if (IN(0)) {
;         LAS float* scr = (LAS float*)(F.lds + F.wave * 16384);
;         const float* nmix = args.in[2]; const float* nffn = args.in[19];
;         constexpr int I_IN = 16 * 160, I_BR = 8 * 32, I_O = 16 * 32, I_G = 16 * 88, I_D = 44 * 32;
;         constexpr int NITEMS = I_IN + 2 * I_BR + I_O + 2 * I_G + I_D;
;         if (sub & 1) for (int it = gw; it < NITEMS; it += NGW) {
;             int r = it;
;             if (r < I_IN) { p0_transpose_item(args.in[3], 1024, 5120, WIN, nmix, 0, scr, r, F.lane); continue; } r -= I_IN;
.LBB0_17:
	s_load_dwordx16 s[16:31], s[0:1], 0x40
	s_load_dwordx16 s[36:51], s[0:1], 0x80
	s_lshr_b32 s58, s12, 6
	v_and_b32_e32 v148, 63, v150
	s_waitcnt lgkmcnt(0)
	v_writelane_b32 v246, s36, 2
	s_nop 1
	v_writelane_b32 v246, s37, 3
	v_writelane_b32 v246, s38, 4
	v_writelane_b32 v246, s39, 5
	v_writelane_b32 v246, s40, 6
	v_writelane_b32 v246, s41, 7
	v_writelane_b32 v246, s42, 8
	v_writelane_b32 v246, s43, 9
	v_writelane_b32 v246, s44, 10
	v_writelane_b32 v246, s45, 11
	v_writelane_b32 v246, s46, 12
	v_writelane_b32 v246, s47, 13
	v_writelane_b32 v246, s48, 14
	v_writelane_b32 v246, s49, 15
	v_writelane_b32 v246, s50, 16
	v_writelane_b32 v246, s51, 17
	s_add_u32 s46, s82, 0x20000
	s_addc_u32 s47, s83, 0
	s_add_u32 s34, s82, 0x60000
	s_addc_u32 s35, s83, 0
	s_add_u32 s0, s82, 0x64000
	s_addc_u32 s1, s83, 0
	v_writelane_b32 v246, s12, 18
	s_add_u32 s10, s82, 0x100000
	v_writelane_b32 v246, s0, 19
	s_addc_u32 s11, s83, 0
	s_nop 0
	v_writelane_b32 v246, s1, 20
	s_add_u32 s0, s82, 0xb00000
	s_addc_u32 s1, s83, 0
	v_writelane_b32 v246, s0, 21
	s_nop 1
	v_writelane_b32 v246, s1, 22
	s_add_u32 s0, s82, 0xc00000
	s_addc_u32 s1, s83, 0
	v_writelane_b32 v246, s0, 23
	s_nop 1
	v_writelane_b32 v246, s1, 24
	s_add_u32 s0, s82, 0xd00000
	s_addc_u32 s1, s83, 0
	s_add_u32 s90, s82, 0xf00000
	v_writelane_b32 v246, s0, 25
	s_addc_u32 s91, s83, 0
	s_nop 0
	v_writelane_b32 v246, s1, 26
	s_add_u32 s0, s82, 0x1a00000
	s_addc_u32 s1, s83, 0
	s_add_u32 s92, s82, 0x2000000
	s_addc_u32 s93, s83, 0
	v_writelane_b32 v246, s0, 27
	s_add_u32 s40, s82, 0xc800000
	s_addc_u32 s41, s83, 0
	v_writelane_b32 v246, s1, 28
	s_lshl_b32 s0, s33, 3
	s_add_i32 s86, s58, s0
	s_lshl_b32 s88, s89, 3
	s_cmp_lt_i32 s84, 1
	s_cselect_b64 s[0:1], -1, 0
	s_cmp_gt_i32 s85, 0
	s_cselect_b64 s[2:3], -1, 0
	s_and_b64 s[12:13], s[0:1], s[2:3]
	s_andn2_b64 vcc, exec, s[12:13]
	v_writelane_b32 v246, s58, 29
	s_mov_b32 s101, 1
	s_cbranch_vccnz .LBB0_361
	s_mov_b32 s101, 0
	s_bitcmp1_b32 s33, 0
	s_cbranch_scc1 .LBB0_172
.Lp0_a_start:
	s_cmpk_gt_i32 s86, 0x1e7f
	s_cbranch_scc1 .LBB0_147
	v_and_b32_e32 v1, 31, v150
	v_lshlrev_b32_e32 v2, 2, v1
	v_lshlrev_b32_e32 v1, 3, v150
	s_lshl_b32 s0, s58, 14
	v_lshrrev_b32_e32 v105, 3, v148
	v_and_b32_e32 v1, 56, v1
	s_add_i32 s2, s0, 0
	v_mul_u32_u24_e32 v6, 0x84, v1
	v_lshlrev_b32_e32 v14, 1, v1
	v_lshlrev_b32_e32 v1, 2, v105
	v_mov_b32_e32 v3, 0
	v_add_u32_e32 v104, s2, v2
	v_add3_u32 v106, s2, v6, v1
	v_readlane_b32 s2, v246, 25
	v_mov_b32_e32 v15, v3
	v_readlane_b32 s3, v246, 26
	v_lshrrev_b32_e32 v0, 5, v148
	v_readlane_b32 s48, v246, 2
	v_lshl_add_u64 v[8:9], s[2:3], 0, v[14:15]
	v_readlane_b32 s2, v246, 23
	v_readlane_b32 s3, v246, 24
	v_mul_u32_u24_e32 v110, 0x84, v0
	v_readlane_b32 s4, v246, 27
	v_readlane_b32 s54, v246, 8
	v_readlane_b32 s55, v246, 9
	v_lshl_add_u64 v[10:11], s[2:3], 0, v[14:15]
	v_readlane_b32 s2, v246, 21
	v_or_b32_e32 v24, s0, v110
	v_readlane_b32 s5, v246, 28
	s_cmp_lg_u64 s[54:55], 0
	v_readlane_b32 s3, v246, 22
	v_add3_u32 v119, v24, v2, 0
	v_mul_u32_u24_e32 v24, 0x2c00, v0
	v_lshlrev_b32_e32 v26, 2, v0
	v_mov_b32_e32 v27, v3
	v_lshl_add_u64 v[4:5], s[4:5], 0, v[14:15]
	v_readlane_b32 s49, v246, 3
	v_readlane_b32 s50, v246, 4
	v_readlane_b32 s51, v246, 5
	v_readlane_b32 s52, v246, 6
	v_readlane_b32 s53, v246, 7
	v_readlane_b32 s56, v246, 10
	v_readlane_b32 s57, v246, 11
	v_readlane_b32 s58, v246, 12
	v_readlane_b32 s59, v246, 13
	v_readlane_b32 s60, v246, 14
	v_readlane_b32 s61, v246, 15
	s_cselect_b64 s[4:5], -1, 0
	v_lshl_add_u64 v[12:13], s[2:3], 0, v[14:15]
	s_cmp_lg_u64 s[68:69], 0
	v_or_b32_e32 v1, 2, v0
	v_or_b32_e32 v17, 6, v0
	v_or_b32_e32 v16, 4, v0
	v_or_b32_e32 v19, 10, v0
	v_or_b32_e32 v18, 8, v0
	v_or_b32_e32 v21, 14, v0
	v_or_b32_e32 v20, 12, v0
	v_or_b32_e32 v23, 18, v0
	v_or_b32_e32 v22, 16, v0
	v_mul_hi_u32_u24_e32 v29, 0x2c00, v0
	v_or_b32_e32 v28, v24, v2
	v_lshl_add_u64 v[26:27], s[54:55], 0, v[26:27]
	s_mov_b64 s[2:3], 0x78
	v_or_b32_e32 v30, 20, v0
	v_or_b32_e32 v31, 22, v0
	v_or_b32_e32 v32, 24, v0
	v_or_b32_e32 v33, 26, v0
	v_or_b32_e32 v34, 28, v0
	v_or_b32_e32 v35, 30, v0
	v_or_b32_e32 v36, 32, v0
	v_or_b32_e32 v37, 34, v0
	v_or_b32_e32 v38, 36, v0
	v_or_b32_e32 v39, 38, v0
	v_or_b32_e32 v40, 40, v0
	v_or_b32_e32 v41, 42, v0
	v_or_b32_e32 v42, 44, v0
	v_or_b32_e32 v43, 46, v0
	v_or_b32_e32 v44, 48, v0
	v_or_b32_e32 v45, 50, v0
	v_or_b32_e32 v46, 52, v0
	v_or_b32_e32 v47, 54, v0
	v_or_b32_e32 v48, 56, v0
	v_or_b32_e32 v49, 58, v0
	v_or_b32_e32 v50, 60, v0
	v_or_b32_e32 v51, 62, v0
	s_mov_b32 s1, 0
	v_or_b32_e32 v107, 8, v105
	v_or_b32_e32 v108, 16, v105
	v_or_b32_e32 v109, 24, v105
	v_lshl_add_u64 v[6:7], s[90:91], 0, v[14:15]
	s_cselect_b64 s[6:7], -1, 0
	v_lshl_add_u64 v[14:15], s[10:11], 0, v[14:15]
	v_mul_u32_u24_e32 v111, 0x84, v1
	v_mul_u32_u24_e32 v112, 0x84, v16
	v_mul_u32_u24_e32 v113, 0x84, v17
	v_mul_u32_u24_e32 v114, 0x84, v18
	v_mul_u32_u24_e32 v115, 0x84, v19
	v_mul_u32_u24_e32 v116, 0x84, v20
	v_mul_u32_u24_e32 v117, 0x84, v21
	v_mul_u32_u24_e32 v118, 0x84, v22
	v_lshl_add_u64 v[24:25], s[58:59], 0, v[28:29]
	v_lshl_add_u64 v[26:27], v[26:27], 0, s[2:3]
	v_lshl_add_u64 v[28:29], s[56:57], 0, v[28:29]
	s_mov_b64 s[8:9], 0x80
	s_movk_i32 s44, 0x5000
	s_mov_b32 s45, s86
	v_mul_u32_u24_e32 v120, 0x84, v23
	v_mul_u32_u24_e32 v121, 0x84, v30
	v_mul_u32_u24_e32 v122, 0x84, v31
	v_mul_u32_u24_e32 v123, 0x84, v32
	v_mul_u32_u24_e32 v124, 0x84, v33
	v_mul_u32_u24_e32 v125, 0x84, v34
	v_mul_u32_u24_e32 v126, 0x84, v35
	v_mul_u32_u24_e32 v127, 0x84, v36
	v_mul_u32_u24_e32 v128, 0x84, v37
	v_mul_u32_u24_e32 v129, 0x84, v38
	v_mul_u32_u24_e32 v130, 0x84, v39
	v_mul_u32_u24_e32 v131, 0x84, v40
	v_mul_u32_u24_e32 v132, 0x84, v41
	v_mul_u32_u24_e32 v133, 0x84, v42
	v_mul_u32_u24_e32 v134, 0x84, v43
	v_mul_u32_u24_e32 v135, 0x84, v44
	v_mul_u32_u24_e32 v136, 0x84, v45
	v_mul_u32_u24_e32 v137, 0x84, v46
	v_mul_u32_u24_e32 v138, 0x84, v47
	v_mul_u32_u24_e32 v139, 0x84, v48
	v_mul_u32_u24_e32 v140, 0x84, v49
	v_mul_u32_u24_e32 v141, 0x84, v50
	v_mul_u32_u24_e32 v142, 0x84, v51
	v_lshl_add_u64 v[52:53], s[60:61], 0, v[2:3]
	v_lshl_add_u64 v[54:55], s[52:53], 0, v[2:3]
	v_lshl_add_u64 v[56:57], s[50:51], 0, v[2:3]
	v_lshl_add_u64 v[58:59], s[48:49], 0, v[2:3]
	v_lshl_add_u64 v[60:61], s[58:59], 0, v[2:3]
	v_readlane_b32 s58, v246, 29
	v_lshl_add_u64 v[62:63], s[56:57], 0, v[2:3]
	v_lshl_add_u64 v[64:65], s[70:71], 0, v[2:3]
	v_readlane_b32 s62, v246, 16
	v_readlane_b32 s63, v246, 17
	s_branch .LBB0_22

; #define LAS __attribute__((address_space(3)))
; DI void filter_stage_weights(const Frame& F, const float* w1, const float* b1, const float* w2, const float* b2, const float* w3, const float* b3, const float* freq) {
;     LAS float* wl = (LAS float*)(F.lds + FLT_WL);
;     for (int i = F.tid; i < 2112; i += 512) wl[i] = w1[i];
; __global__ void __launch_bounds__(512, 2) hybrid_fwd(Args args) {
;     ...
;         __syncthreads();
;         if (sub == 3 || (sub & 4)) filter_stage_weights(F, args.in[7], args.in[8], args.in[9], args.in[10], args.in[11], args.in[12], args.in[14]);
;         if (sub == 3 || (sub & 4)) {
;             for (int fu = F.bid; fu < 256; fu += F.G) filter_unit(F, 16384, 64 * fu, FRS, F0 + 1024, args.in[13], 0, 4);
.LBB0_172:
	s_cmp_lg_u32 s101, 0
	s_cbranch_scc1 .LBB0_361
	v_lshlrev_b32_e32 v6, 2, v150
	v_add_u32_e32 v8, 0, v6
	v_mov_b32_e32 v7, 0
	v_add_u32_e32 v2, 0xc800, v8
	v_lshl_add_u64 v[0:1], s[78:79], 0, v[6:7]
	v_add_u32_e32 v3, 0xfffffe00, v150
	s_mov_b64 s[0:1], 0
	s_mov_b64 s[2:3], 0x800
	s_movk_i32 s4, 0x63f
	s_waitcnt lgkmcnt(0)
	s_barrier

; __global__ void __launch_bounds__(512, 2) hybrid_fwd(Args args) {
;     ...
;         if (sub == 3 || (sub & 4)) filter_stage_weights(F, args.in[7], args.in[8], args.in[9], args.in[10], args.in[11], args.in[12], args.in[14]);
;         if (sub == 3 || (sub & 4)) {
;             for (int fu = F.bid; fu < 256; fu += F.G) filter_unit(F, 16384, 64 * fu, FRS, F0 + 1024, args.in[13], 0, 4);
;             for (int fq = F.bid; fq < 256; fq += F.G) filter_unit(F, 4096, 64 * (fq >> 2), FRP, F0, args.in[13], 8 * (fq & 3), 1);
;         }
;     }
.LBB0_361:
	s_cmp_lg_u32 s101, 0
	s_cbranch_scc1 .Lp0_done
	s_bitcmp1_b32 s33, 0
	s_cbranch_scc0 .Lp0_done
	s_mov_b32 s101, 1
	s_branch .Lp0_a_start

; #define PG8_STAGE(bufoff, gbase, voff) do { _Pragma("unroll") for (int _i = 0; _i < 2; ++_i) \
;         __builtin_amdgcn_global_load_lds((const unsigned*)((const char*)(gbase) + (voff)[_i]), (PG8_LAS unsigned*)(lds + (bufoff) + ldsw + _i * 8192), 16, 0, 0); } while (0)
; #define PG8_WAIT_V(n) asm volatile("s_waitcnt vmcnt(" #n ")" ::: "memory")
; #define PG8_BAR __builtin_amdgcn_s_barrier()
; template <class Epi, class Sched, bool ALIGN_EPI = false, bool SP2 = false>
; __device__ __forceinline__ void gemm_phase(PG8_LAS unsigned char* lds, const Gemm g, const Sched& S, const Epi& E) {
;     ...
;     const unsigned ldsw = (unsigned)wid * 1024u;
;     const int aoff = lds_byte(wr * 64 + fr, fq * 8), boff = lds_byte(wc * 32 + fr, fq * 8);
;     ...
;         PG8_WAIT_V(2); PG8_BAR;
;         PG8_STAGE(PG8_SB(1, 0), cB + kstep, voffB); PG8_STAGE(PG8_SA(1, 0), cA + kstep, voffA); PG8_STAGE(PG8_SB(1, 1), cB + hstep + kstep, voffB);
;         PG8_WAIT_V(6); PG8_BAR;
.LBB0_421:
	s_lshl_b32 s3, s3, 5
	s_mov_b64 s[16:17], 0x80
	s_and_b32 s3, s3, 0x60
	s_add_i32 m0, s63, 0x18000
	v_lshl_add_u64 v[6:7], v[6:7], 0, s[16:17]
	s_lshl_b32 s5, s2, 13
	s_lshl_b32 s7, s3, 7
	global_load_lds_dwordx4 v[6:7], off
	v_lshl_add_u64 v[4:5], v[4:5], 0, s[16:17]
	s_add_i32 m0, s63, 0x1a000
	s_add_i32 s69, s63, 0x8000
	s_add_i32 s70, s63, 0xa000
	global_load_lds_dwordx4 v[4:5], off
	v_lshl_add_u64 v[0:1], v[0:1], 0, s[16:17]
	s_mov_b32 m0, s69
	s_add_u32 s18, s28, 0x40080
	global_load_lds_dwordx4 v[0:1], off
	v_lshl_add_u64 v[0:1], v[2:3], 0, s[16:17]
	s_mov_b32 m0, s70
	s_addc_u32 s19, s29, 0
	global_load_lds_dwordx4 v[0:1], off
	s_add_i32 m0, s63, 0x1c000
	v_lshl_add_u64 v[0:1], s[18:19], 0, v[130:131]
	global_load_lds_dwordx4 v[0:1], off
	v_lshl_add_u64 v[0:1], s[18:19], 0, v[134:135]
	s_add_i32 m0, s63, 0x1e000
	v_lshlrev_b32_e32 v2, 2, v150
	global_load_lds_dwordx4 v[0:1], off
	s_waitcnt vmcnt(8)
	s_barrier
	v_and_b32_e32 v0, 15, v150
	v_lshl_or_b32 v139, s2, 6, v0
	v_lshlrev_b32_e32 v1, 1, v12
	v_lshlrev_b32_e32 v3, 6, v150
	s_movk_i32 s2, 0x3c0
	v_lshl_or_b32 v0, v0, 6, v1
	v_and_b32_e32 v2, 32, v2
	v_and_or_b32 v1, v3, s2, v1
	v_bitop3_b32 v149, s7, v1, v2 bitop3:0xf6
	v_lshlrev_b32_e32 v1, 8, v150
	v_bitop3_b32 v0, v0, s5, v2 bitop3:0xde
	v_and_b32_e32 v1, 0x38000, v1
	v_lshlrev_b32_e32 v2, 11, v10
	v_or3_b32 v1, v8, v1, v2
	v_add_u32_e32 v140, v1, v9
	v_lshlrev_b32_e32 v1, 4, v11
	s_waitcnt vmcnt(6)
	s_cmpk_lt_u32 s12, 0x100
	v_and_b32_e32 v1, 0x78000, v1
	s_cselect_b64 s[18:19], -1, 0
	v_or_b32_e32 v138, s3, v12
	v_or3_b32 v1, v8, v1, v2
	s_add_i32 s79, 0, 0x10000
	s_add_i32 s84, 0, 0x14000
	v_or_b32_e32 v151, 0x80, v138
	s_ashr_i32 s71, s89, 31
	s_ashr_i32 s78, s33, 31
	v_mov_b32_e32 v141, v137
	v_add_u32_e32 v142, v1, v9
	v_mov_b32_e32 v143, v137
	v_mov_b64_e32 v[144:145], 0x600
	v_mov_b64_e32 v[146:147], 0x5ff
	v_add_u32_e32 v162, s79, v149
	v_add_u32_e32 v163, s84, v149
	v_add_u32_e32 v164, 0, v0
	v_mov_b32_e32 v165, 0x358637bd
	s_mov_b32 s85, 0x800000
	s_movk_i32 s87, 0xc00
	s_mov_b32 s97, 0
	s_barrier
	s_branch .LBB0_424

; #define PG8_STAGE(bufoff, gbase, voff) do { _Pragma("unroll") for (int _i = 0; _i < 2; ++_i) \
;         __builtin_amdgcn_global_load_lds((const unsigned*)((const char*)(gbase) + (voff)[_i]), (PG8_LAS unsigned*)(lds + (bufoff) + ldsw + _i * 8192), 16, 0, 0); } while (0)
; #define PG8_WAIT_V(n) asm volatile("s_waitcnt vmcnt(" #n ")" ::: "memory")
; #define PG8_BAR __builtin_amdgcn_s_barrier()
; template <class Epi, class Sched, bool ALIGN_EPI = false, bool SP2 = false>
; __device__ __forceinline__ void gemm_phase(PG8_LAS unsigned char* lds, const Gemm g, const Sched& S, const Epi& E) {
;     ...
;     const unsigned ldsw = (unsigned)wid * 1024u;
;     const int aoff = lds_byte(wr * 64 + fr, fq * 8), boff = lds_byte(wc * 32 + fr, fq * 8);
;     ...
;         PG8_WAIT_V(2); PG8_BAR;
;         PG8_STAGE(PG8_SB(1, 0), cB + kstep, voffB); PG8_STAGE(PG8_SA(1, 0), cA + kstep, voffA); PG8_STAGE(PG8_SB(1, 1), cB + hstep + kstep, voffB);
;         PG8_WAIT_V(6); PG8_BAR;
.LBB0_1237:
	s_mov_b64 s[18:19], 0x80
	s_lshl_b32 s1, s9, 5
	s_add_i32 m0, s40, 0x18000
	v_lshl_add_u64 v[6:7], v[6:7], 0, s[18:19]
	s_lshl_b32 s20, s8, 13
	s_and_b32 s9, s1, 0x60
	global_load_lds_dwordx4 v[6:7], off
	v_lshl_add_u64 v[2:3], v[2:3], 0, s[18:19]
	s_add_i32 m0, s40, 0x1a000
	s_add_i32 s45, s40, 0x8000
	s_add_i32 s50, s40, 0xa000
	global_load_lds_dwordx4 v[2:3], off
	v_lshl_add_u64 v[0:1], v[0:1], 0, s[18:19]
	s_mov_b32 m0, s45
	s_add_u32 s10, s6, 0x40080
	global_load_lds_dwordx4 v[0:1], off
	v_lshl_add_u64 v[0:1], v[4:5], 0, s[18:19]
	s_mov_b32 m0, s50
	s_addc_u32 s11, s7, 0
	global_load_lds_dwordx4 v[0:1], off
	s_add_i32 m0, s40, 0x1c000
	v_lshl_add_u64 v[0:1], s[10:11], 0, v[130:131]
	global_load_lds_dwordx4 v[0:1], off
	v_lshl_add_u64 v[0:1], s[10:11], 0, v[134:135]
	s_add_i32 m0, s40, 0x1e000
	v_lshlrev_b32_e32 v2, 11, v164
	global_load_lds_dwordx4 v[0:1], off
	s_waitcnt vmcnt(8)
	s_barrier
	v_lshlrev_b32_e32 v1, 2, v167
	v_lshl_or_b32 v0, v167, 6, v168
	v_and_b32_e32 v1, 32, v1
	v_bitop3_b32 v0, v0, s20, v1 bitop3:0xde
	v_lshlrev_b32_e32 v1, 8, v150
	v_and_b32_e32 v1, 0x38000, v1
	v_or3_b32 v1, v149, v1, v2
	v_add_u32_e32 v136, v1, v151
	v_lshlrev_b32_e32 v1, 4, v166
	s_waitcnt vmcnt(6)
	s_cmpk_lt_u32 s3, 0x100
	v_and_b32_e32 v1, 0x78000, v1
	v_lshl_or_b32 v161, s9, 7, v169
	s_cselect_b64 s[20:21], -1, 0
	v_or3_b32 v1, v149, v1, v2
	s_add_i32 s60, 0, 0x10000
	s_add_i32 s61, 0, 0x14000
	s_sext_i32_i8 s1, s2
	v_lshl_or_b32 v160, s8, 6, v167
	s_ashr_i32 s51, s89, 31
	v_or_b32_e32 v162, s9, v165
	v_mov_b32_e32 v137, v131
	v_add_u32_e32 v138, v1, v151
	v_mov_b32_e32 v139, v131
	v_mov_b64_e32 v[140:141], 0x200
	v_mov_b64_e32 v[142:143], 0x1ff
	v_add_u32_e32 v163, s60, v161
	v_add_u32_e32 v170, s61, v161
	v_add_u32_e32 v171, 0, v0
	v_mov_b32_e32 v172, 0x358637bd
	s_mov_b32 s62, 0x800000
	s_mov_b64 s[22:23], 0x50000
	s_mov_b32 s63, 0x50000
	s_mov_b64 s[24:25], 0x58000
	s_mov_b32 s68, 0x58000
	s_barrier
	s_branch .LBB0_1240

; #define PG8_STAGE(bufoff, gbase, voff) do { _Pragma("unroll") for (int _i = 0; _i < 2; ++_i) \
;         __builtin_amdgcn_global_load_lds((const unsigned*)((const char*)(gbase) + (voff)[_i]), (PG8_LAS unsigned*)(lds + (bufoff) + ldsw + _i * 8192), 16, 0, 0); } while (0)
; #define PG8_WAIT_V(n) asm volatile("s_waitcnt vmcnt(" #n ")" ::: "memory")
; #define PG8_BAR __builtin_amdgcn_s_barrier()
; template <class Epi, class Sched, bool ALIGN_EPI = false, bool SP2 = false>
; __device__ __forceinline__ void gemm_phase(PG8_LAS unsigned char* lds, const Gemm g, const Sched& S, const Epi& E) {
;     ...
;     const unsigned ldsw = (unsigned)wid * 1024u;
;     const int aoff = lds_byte(wr * 64 + fr, fq * 8), boff = lds_byte(wc * 32 + fr, fq * 8);
;     ...
;         PG8_WAIT_V(2); PG8_BAR;
;         PG8_STAGE(PG8_SB(1, 0), cB + kstep, voffB); PG8_STAGE(PG8_SA(1, 0), cA + kstep, voffA); PG8_STAGE(PG8_SB(1, 1), cB + hstep + kstep, voffB);
;         PG8_WAIT_V(6); PG8_BAR;
.LBB0_1261:
	s_lshl_b32 s6, s6, 5
	s_and_b32 s12, s6, 0x60
	s_mov_b64 s[6:7], 0x80
	s_add_i32 m0, s27, 0x18000
	v_lshl_add_u64 v[6:7], v[6:7], 0, s[6:7]
	s_lshl_b32 s9, s8, 13
	global_load_lds_dwordx4 v[6:7], off
	v_lshl_add_u64 v[4:5], v[4:5], 0, s[6:7]
	s_add_i32 m0, s27, 0x1a000
	s_add_i32 s42, s27, 0x8000
	s_add_i32 s43, s27, 0xa000
	global_load_lds_dwordx4 v[4:5], off
	v_lshl_add_u64 v[0:1], v[0:1], 0, s[6:7]
	s_mov_b32 m0, s42
	s_add_u32 s10, s30, 0x20080
	global_load_lds_dwordx4 v[0:1], off
	v_lshl_add_u64 v[0:1], v[2:3], 0, s[6:7]
	s_mov_b32 m0, s43
	s_addc_u32 s11, s31, 0
	global_load_lds_dwordx4 v[0:1], off
	s_add_i32 m0, s27, 0x1c000
	v_lshl_add_u64 v[0:1], s[10:11], 0, v[138:139]
	global_load_lds_dwordx4 v[0:1], off
	v_lshl_add_u64 v[0:1], s[10:11], 0, v[142:143]
	s_add_i32 m0, s27, 0x1e000
	v_lshlrev_b32_e32 v2, 10, v164
	global_load_lds_dwordx4 v[0:1], off
	s_waitcnt vmcnt(8)
	s_barrier
	v_lshlrev_b32_e32 v1, 2, v167
	v_lshl_or_b32 v0, v167, 6, v168
	v_and_b32_e32 v1, 32, v1
	v_bitop3_b32 v0, v0, s9, v1 bitop3:0xde
	v_lshlrev_b32_e32 v1, 7, v150
	v_and_b32_e32 v1, 0x1c000, v1
	v_or3_b32 v1, v149, v1, v2
	v_add_u32_e32 v144, v1, v151
	v_lshlrev_b32_e32 v1, 3, v166
	s_waitcnt vmcnt(6)
	s_cmpk_lt_u32 s5, 0x100
	v_and_b32_e32 v1, 0x3c000, v1
	v_lshl_or_b32 v129, s8, 6, v167
	v_lshl_or_b32 v131, s12, 7, v169
	s_cselect_b64 s[8:9], -1, 0
	v_or3_b32 v1, v149, v1, v2
	s_add_i32 s45, 0, 0x10000
	s_add_i32 s50, 0, 0x14000
	s_sext_i32_i8 s60, s4
	s_ashr_i32 s44, s89, 31
	v_or_b32_e32 v133, s12, v165
	v_mov_b32_e32 v145, v139
	v_add_u32_e32 v146, v1, v151
	v_mov_b32_e32 v147, v139
	v_mov_b64_e32 v[152:153], 0x200
	v_mov_b64_e32 v[154:155], 0x1ff
	v_add_u32_e32 v135, s45, v131
	v_add_u32_e32 v162, s50, v131
	v_add_u32_e32 v163, 0, v0
	s_mov_b64 s[10:11], 0x48000
	s_mov_b32 s51, 0x48000
	s_mov_b64 s[12:13], 0x50000
	s_mov_b32 s52, 0x50000
	s_mov_b64 s[16:17], 0x58000
	s_mov_b32 s53, 0x58000
	s_barrier
	s_branch .LBB0_1264

; #define PG8_STAGE(bufoff, gbase, voff) do { _Pragma("unroll") for (int _i = 0; _i < 2; ++_i) \
;         __builtin_amdgcn_global_load_lds((const unsigned*)((const char*)(gbase) + (voff)[_i]), (PG8_LAS unsigned*)(lds + (bufoff) + ldsw + _i * 8192), 16, 0, 0); } while (0)
; #define PG8_WAIT_V(n) asm volatile("s_waitcnt vmcnt(" #n ")" ::: "memory")
; #define PG8_BAR __builtin_amdgcn_s_barrier()
; template <class Epi, class Sched, bool ALIGN_EPI = false, bool SP2 = false>
; __device__ __forceinline__ void gemm_phase(PG8_LAS unsigned char* lds, const Gemm g, const Sched& S, const Epi& E) {
;     ...
;     const unsigned ldsw = (unsigned)wid * 1024u;
;     const int aoff = lds_byte(wr * 64 + fr, fq * 8), boff = lds_byte(wc * 32 + fr, fq * 8);
;     ...
;         PG8_WAIT_V(2); PG8_BAR;
;         PG8_STAGE(PG8_SB(1, 0), cB + kstep, voffB); PG8_STAGE(PG8_SA(1, 0), cA + kstep, voffA); PG8_STAGE(PG8_SB(1, 1), cB + hstep + kstep, voffB);
;         PG8_WAIT_V(6); PG8_BAR;
.LBB0_1285:
	s_mov_b64 s[18:19], 0x80
	s_lshl_b32 s1, s11, 5
	s_add_i32 m0, s40, 0x18000
	v_lshl_add_u64 v[6:7], v[6:7], 0, s[18:19]
	s_lshl_b32 s20, s10, 13
	s_and_b32 s11, s1, 0x60
	global_load_lds_dwordx4 v[6:7], off
	v_lshl_add_u64 v[2:3], v[2:3], 0, s[18:19]
	s_add_i32 m0, s40, 0x1a000
	s_add_i32 s45, s40, 0x8000
	s_add_i32 s50, s40, 0xa000
	global_load_lds_dwordx4 v[2:3], off
	v_lshl_add_u64 v[0:1], v[0:1], 0, s[18:19]
	s_mov_b32 m0, s45
	s_add_u32 s12, s8, 0x40080
	global_load_lds_dwordx4 v[0:1], off
	v_lshl_add_u64 v[0:1], v[4:5], 0, s[18:19]
	s_mov_b32 m0, s50
	s_addc_u32 s13, s9, 0
	global_load_lds_dwordx4 v[0:1], off
	s_add_i32 m0, s40, 0x1c000
	v_lshl_add_u64 v[0:1], s[12:13], 0, v[130:131]
	global_load_lds_dwordx4 v[0:1], off
	v_lshl_add_u64 v[0:1], s[12:13], 0, v[134:135]
	s_add_i32 m0, s40, 0x1e000
	v_lshlrev_b32_e32 v2, 11, v164
	global_load_lds_dwordx4 v[0:1], off
	s_waitcnt vmcnt(8)
	s_barrier
	v_lshlrev_b32_e32 v1, 2, v167
	v_lshl_or_b32 v0, v167, 6, v168
	v_and_b32_e32 v1, 32, v1
	v_bitop3_b32 v0, v0, s20, v1 bitop3:0xde
	v_lshlrev_b32_e32 v1, 8, v150
	v_and_b32_e32 v1, 0x38000, v1
	v_or3_b32 v1, v149, v1, v2
	v_add_u32_e32 v144, v1, v151
	v_lshlrev_b32_e32 v1, 4, v166
	s_waitcnt vmcnt(6)
	s_cmpk_lt_u32 s5, 0x100
	v_and_b32_e32 v1, 0x78000, v1
	v_lshl_or_b32 v139, s11, 7, v169
	s_cselect_b64 s[20:21], -1, 0
	v_or3_b32 v1, v149, v1, v2
	s_add_i32 s56, 0, 0x10000
	s_add_i32 s57, 0, 0x14000
	s_sext_i32_i8 s1, s4
	v_lshl_or_b32 v137, s10, 6, v167
	s_ashr_i32 s51, s89, 31
	v_or_b32_e32 v141, s11, v165
	v_mov_b32_e32 v145, v131
	v_add_u32_e32 v146, v1, v151
	v_mov_b32_e32 v147, v131
	v_mov_b64_e32 v[152:153], 0x200
	v_mov_b64_e32 v[154:155], 0x1ff
	v_add_u32_e32 v143, s56, v139
	v_add_u32_e32 v161, s57, v139
	v_add_u32_e32 v170, 0, v0
	v_mov_b32_e32 v171, 0x358637bd
	s_mov_b32 s60, 0x800000
	s_mov_b32 s61, 0x48000
	s_mov_b64 s[22:23], 0x50000
	s_mov_b32 s62, 0x50000
	s_mov_b64 s[24:25], 0x58000
	s_mov_b32 s63, 0x58000
	s_barrier
	s_branch .LBB0_1288

; #define PG8_STAGE(bufoff, gbase, voff) do { _Pragma("unroll") for (int _i = 0; _i < 2; ++_i) \
;         __builtin_amdgcn_global_load_lds((const unsigned*)((const char*)(gbase) + (voff)[_i]), (PG8_LAS unsigned*)(lds + (bufoff) + ldsw + _i * 8192), 16, 0, 0); } while (0)
; #define PG8_WAIT_V(n) asm volatile("s_waitcnt vmcnt(" #n ")" ::: "memory")
; #define PG8_BAR __builtin_amdgcn_s_barrier()
; template <class Epi, class Sched, bool ALIGN_EPI = false, bool SP2 = false>
; __device__ __forceinline__ void gemm_phase(PG8_LAS unsigned char* lds, const Gemm g, const Sched& S, const Epi& E) {
;     ...
;     const unsigned ldsw = (unsigned)wid * 1024u;
;     const int aoff = lds_byte(wr * 64 + fr, fq * 8), boff = lds_byte(wc * 32 + fr, fq * 8);
;     ...
;         PG8_WAIT_V(2); PG8_BAR;
;         PG8_STAGE(PG8_SB(1, 0), cB + kstep, voffB); PG8_STAGE(PG8_SA(1, 0), cA + kstep, voffA); PG8_STAGE(PG8_SB(1, 1), cB + hstep + kstep, voffB);
;         PG8_WAIT_V(6); PG8_BAR;
.LBB0_1309:
	s_lshl_b32 s4, s4, 5
	s_and_b32 s10, s4, 0x60
	s_mov_b64 s[4:5], 0x80
	s_add_i32 m0, s29, 0x18000
	v_lshl_add_u64 v[6:7], v[6:7], 0, s[4:5]
	s_lshl_b32 s7, s6, 13
	global_load_lds_dwordx4 v[6:7], off
	v_lshl_add_u64 v[4:5], v[4:5], 0, s[4:5]
	s_add_i32 m0, s29, 0x1a000
	s_add_i32 s44, s29, 0x8000
	s_add_i32 s45, s29, 0xa000
	global_load_lds_dwordx4 v[4:5], off
	v_lshl_add_u64 v[0:1], v[0:1], 0, s[4:5]
	s_mov_b32 m0, s44
	s_add_u32 s8, s34, 0x20080
	global_load_lds_dwordx4 v[0:1], off
	v_lshl_add_u64 v[0:1], v[2:3], 0, s[4:5]
	s_mov_b32 m0, s45
	s_addc_u32 s9, s35, 0
	global_load_lds_dwordx4 v[0:1], off
	s_add_i32 m0, s29, 0x1c000
	v_lshl_add_u64 v[0:1], s[8:9], 0, v[138:139]
	global_load_lds_dwordx4 v[0:1], off
	v_lshl_add_u64 v[0:1], s[8:9], 0, v[142:143]
	s_add_i32 m0, s29, 0x1e000
	v_lshlrev_b32_e32 v2, 10, v164
	global_load_lds_dwordx4 v[0:1], off
	s_waitcnt vmcnt(8)
	s_barrier
	v_lshlrev_b32_e32 v1, 2, v167
	v_lshl_or_b32 v0, v167, 6, v168
	v_and_b32_e32 v1, 32, v1
	v_bitop3_b32 v0, v0, s7, v1 bitop3:0xde
	v_lshlrev_b32_e32 v1, 7, v150
	v_and_b32_e32 v1, 0x1c000, v1
	v_or3_b32 v1, v149, v1, v2
	v_add_u32_e32 v128, v1, v151
	v_lshlrev_b32_e32 v1, 3, v166
	s_waitcnt vmcnt(6)
	s_cmpk_lt_u32 s3, 0x100
	v_and_b32_e32 v1, 0x3c000, v1
	v_lshl_or_b32 v156, s6, 6, v167
	v_lshl_or_b32 v157, s10, 7, v169
	s_cselect_b64 s[6:7], -1, 0
	v_or3_b32 v1, v149, v1, v2
	s_add_i32 s51, 0, 0x10000
	s_add_i32 s56, 0, 0x14000
	s_sext_i32_i8 s52, s2
	s_ashr_i32 s50, s89, 31
	v_or_b32_e32 v158, s10, v165
	v_mov_b32_e32 v129, v139
	v_add_u32_e32 v130, v1, v151
	v_mov_b32_e32 v131, v139
	v_mov_b64_e32 v[132:133], 0x200
	v_mov_b64_e32 v[134:135], 0x1ff
	v_add_u32_e32 v149, s51, v157
	v_add_u32_e32 v151, s56, v157
	v_add_u32_e32 v159, 0, v0
	s_mov_b64 s[8:9], 0x48100
	s_mov_b32 s57, 0x48000
	s_mov_b64 s[10:11], 0x50000
	s_mov_b64 s[12:13], 0x50100
	s_mov_b32 s60, 0x50000
	s_mov_b64 s[16:17], 0x58000
	s_mov_b64 s[18:19], 0x58100
	s_mov_b32 s61, 0x58000
	s_barrier
	s_branch .LBB0_1312

; #define PG8_STAGE(bufoff, gbase, voff) do { _Pragma("unroll") for (int _i = 0; _i < 2; ++_i) \
;         __builtin_amdgcn_global_load_lds((const unsigned*)((const char*)(gbase) + (voff)[_i]), (PG8_LAS unsigned*)(lds + (bufoff) + ldsw + _i * 8192), 16, 0, 0); } while (0)
; #define PG8_WAIT_V(n) asm volatile("s_waitcnt vmcnt(" #n ")" ::: "memory")
; #define PG8_BAR __builtin_amdgcn_s_barrier()
; template <class Epi, class Sched, bool ALIGN_EPI = false, bool SP2 = false>
; __device__ __forceinline__ void gemm_phase(PG8_LAS unsigned char* lds, const Gemm g, const Sched& S, const Epi& E) {
;     ...
;     const unsigned ldsw = (unsigned)wid * 1024u;
;     const int aoff = lds_byte(wr * 64 + fr, fq * 8), boff = lds_byte(wc * 32 + fr, fq * 8);
;     ...
;         PG8_WAIT_V(2); PG8_BAR;
;         PG8_STAGE(PG8_SB(1, 0), cB + kstep, voffB); PG8_STAGE(PG8_SA(1, 0), cA + kstep, voffA); PG8_STAGE(PG8_SB(1, 1), cB + hstep + kstep, voffB);
;         PG8_WAIT_V(6); PG8_BAR;
.LBB0_1390:
	s_lshl_b32 s3, s3, 5
	s_mov_b64 s[8:9], 0x80
	s_and_b32 s12, s3, 0x60
	s_add_i32 m0, s23, 0x18000
	v_lshl_add_u64 v[6:7], v[6:7], 0, s[8:9]
	s_lshl_b32 s11, s2, 13
	s_lshl_b32 s3, s12, 7
	global_load_lds_dwordx4 v[6:7], off
	v_lshl_add_u64 v[4:5], v[4:5], 0, s[8:9]
	s_add_i32 m0, s23, 0x1a000
	s_add_i32 s38, s23, 0x8000
	s_add_i32 s39, s23, 0xa000
	global_load_lds_dwordx4 v[4:5], off
	v_lshl_add_u64 v[2:3], v[2:3], 0, s[8:9]
	s_mov_b32 m0, s38
	s_add_u32 s4, s26, 0x40080
	global_load_lds_dwordx4 v[2:3], off
	v_lshl_add_u64 v[0:1], v[0:1], 0, s[8:9]
	s_mov_b32 m0, s39
	s_addc_u32 s5, s27, 0
	global_load_lds_dwordx4 v[0:1], off
	s_add_i32 m0, s23, 0x1c000
	v_lshl_add_u64 v[0:1], s[4:5], 0, v[128:129]
	global_load_lds_dwordx4 v[0:1], off
	v_lshl_add_u64 v[0:1], s[4:5], 0, v[130:131]
	s_add_i32 m0, s23, 0x1e000
	v_lshlrev_b32_e32 v3, 2, v150
	global_load_lds_dwordx4 v[0:1], off
	s_waitcnt vmcnt(8)
	s_barrier
	v_and_b32_e32 v0, 15, v150
	v_bfe_u32 v1, v150, 4, 2
	v_lshl_or_b32 v144, s2, 6, v0
	v_lshlrev_b32_e32 v2, 4, v1
	v_lshlrev_b32_e32 v4, 6, v150
	s_movk_i32 s2, 0x3c0
	v_lshl_or_b32 v0, v0, 6, v2
	v_and_b32_e32 v3, 32, v3
	v_and_or_b32 v2, v4, s2, v2
	v_bitop3_b32 v145, s3, v2, v3 bitop3:0xf6
	v_cmp_eq_u32_e64 s[2:3], 0, v1
	v_lshl_or_b32 v146, v1, 2, s12
	v_lshlrev_b32_e32 v1, 8, v150
	v_and_b32_e32 v1, 0x38000, v1
	v_lshlrev_b32_e32 v2, 11, v10
	v_or3_b32 v1, v8, v1, v2
	v_add_u32_e32 v132, v1, v9
	v_lshlrev_b32_e32 v1, 4, v11
	v_bitop3_b32 v0, v0, s11, v3 bitop3:0xde
	s_waitcnt vmcnt(6)
	s_cmpk_lt_u32 s10, 0x100
	v_and_b32_e32 v1, 0x78000, v1
	s_cselect_b64 s[10:11], -1, 0
	v_or3_b32 v1, v8, v1, v2
	s_add_i32 s42, 0, 0x10000
	s_add_i32 s43, 0, 0x14000
	v_add_u32_e32 v151, 0, v0
	v_mbcnt_lo_u32_b32 v0, -1, 0
	s_ashr_i32 s40, s89, 31
	s_ashr_i32 s41, s33, 31
	v_mov_b32_e32 v133, v129
	v_add_u32_e32 v134, v1, v9
	v_mov_b32_e32 v135, v129
	v_mov_b64_e32 v[136:137], 0x200
	v_mov_b64_e32 v[138:139], 0x1ff
	v_add_u32_e32 v147, s42, v145
	v_add_u32_e32 v149, s43, v145
	v_mbcnt_hi_u32_b32 v152, -1, v0
	s_movk_i32 s44, 0x3ff0
	s_movk_i32 s45, 0x3fe0
	s_movk_i32 s50, 0x3fd0
	s_movk_i32 s51, 0x3f80
	s_movk_i32 s52, 0x3f70
	s_movk_i32 s53, 0x3f60
	s_movk_i32 s56, 0x3f50
	s_barrier
	s_branch .LBB0_1393

; #define PG8_STAGE(bufoff, gbase, voff) do { _Pragma("unroll") for (int _i = 0; _i < 2; ++_i) \
;         __builtin_amdgcn_global_load_lds((const unsigned*)((const char*)(gbase) + (voff)[_i]), (PG8_LAS unsigned*)(lds + (bufoff) + ldsw + _i * 8192), 16, 0, 0); } while (0)
; #define PG8_WAIT_V(n) asm volatile("s_waitcnt vmcnt(" #n ")" ::: "memory")
; #define PG8_BAR __builtin_amdgcn_s_barrier()
; template <class Epi, class Sched, bool ALIGN_EPI = false, bool SP2 = false>
; __device__ __forceinline__ void gemm_phase(PG8_LAS unsigned char* lds, const Gemm g, const Sched& S, const Epi& E) {
;     ...
;     const unsigned ldsw = (unsigned)wid * 1024u;
;     const int aoff = lds_byte(wr * 64 + fr, fq * 8), boff = lds_byte(wc * 32 + fr, fq * 8);
;     ...
;         PG8_WAIT_V(2); PG8_BAR;
;         PG8_STAGE(PG8_SB(1, 0), cB + kstep, voffB); PG8_STAGE(PG8_SA(1, 0), cA + kstep, voffA); PG8_STAGE(PG8_SB(1, 1), cB + hstep + kstep, voffB);
;         PG8_WAIT_V(6); PG8_BAR;
.LBB0_1481:
	s_lshl_b32 s1, s9, 5
	s_mov_b64 s[16:17], 0x80
	s_and_b32 s9, s1, 0x60
	s_add_i32 m0, s31, 0x18000
	v_lshl_add_u64 v[6:7], v[6:7], 0, s[16:17]
	s_lshl_b32 s18, s8, 13
	s_lshl_b32 s19, s9, 7
	global_load_lds_dwordx4 v[6:7], off
	v_lshl_add_u64 v[4:5], v[4:5], 0, s[16:17]
	s_add_i32 m0, s31, 0x1a000
	s_add_i32 s38, s31, 0x8000
	s_add_i32 s39, s31, 0xa000
	global_load_lds_dwordx4 v[4:5], off
	v_lshl_add_u64 v[0:1], v[0:1], 0, s[16:17]
	s_mov_b32 m0, s38
	s_add_u32 s10, s6, 0x40080
	global_load_lds_dwordx4 v[0:1], off
	v_lshl_add_u64 v[0:1], v[2:3], 0, s[16:17]
	s_mov_b32 m0, s39
	s_addc_u32 s11, s7, 0
	global_load_lds_dwordx4 v[0:1], off
	s_add_i32 m0, s31, 0x1c000
	v_lshl_add_u64 v[0:1], s[10:11], 0, v[132:133]
	global_load_lds_dwordx4 v[0:1], off
	v_lshl_add_u64 v[0:1], s[10:11], 0, v[128:129]
	s_add_i32 m0, s31, 0x1e000
	s_sext_i32_i16 s1, s2
	global_load_lds_dwordx4 v[0:1], off
	s_waitcnt vmcnt(8)
	s_barrier
	v_and_b32_e32 v0, 15, v150
	v_lshlrev_b32_e32 v1, 1, v11
	v_lshlrev_b32_e32 v2, 2, v150
	v_lshlrev_b32_e32 v3, 6, v150
	s_movk_i32 s2, 0x3c0
	v_lshl_or_b32 v149, s8, 6, v0
	v_lshl_or_b32 v0, v0, 6, v1
	v_and_b32_e32 v2, 32, v2
	v_and_or_b32 v1, v3, s2, v1
	v_bitop3_b32 v151, s19, v1, v2 bitop3:0xf6
	v_lshlrev_b32_e32 v1, 8, v150
	v_bitop3_b32 v0, v0, s18, v2 bitop3:0xde
	v_and_b32_e32 v1, 0x38000, v1
	v_lshlrev_b32_e32 v2, 11, v12
	v_or3_b32 v1, v9, v1, v2
	v_add_u32_e32 v136, v1, v10
	v_lshlrev_b32_e32 v1, 4, v8
	s_waitcnt vmcnt(6)
	s_cmpk_lt_u32 s3, 0x100
	v_and_b32_e32 v1, 0x78000, v1
	s_cselect_b64 s[18:19], -1, 0
	v_or3_b32 v1, v9, v1, v2
	s_add_i32 s41, 0, 0x10000
	s_add_i32 s42, 0, 0x14000
	s_ashr_i32 s40, s89, 31
	v_or_b32_e32 v154, s9, v11
	v_mov_b32_e32 v137, v133
	v_add_u32_e32 v138, v1, v10
	v_mov_b32_e32 v139, v133
	v_mov_b64_e32 v[140:141], 0x580
	v_mov_b64_e32 v[142:143], 0x57f
	v_add_u32_e32 v155, s41, v151
	v_add_u32_e32 v156, s42, v151
	v_add_u32_e32 v157, 0, v0
	v_mov_b32_e32 v158, 0x358637bd
	s_mov_b32 s43, 0x800000
	s_movk_i32 s44, 0x1600
	s_barrier
	s_branch .LBB0_1484

; #define PG8_STAGE(bufoff, gbase, voff) do { _Pragma("unroll") for (int _i = 0; _i < 2; ++_i) \
;         __builtin_amdgcn_global_load_lds((const unsigned*)((const char*)(gbase) + (voff)[_i]), (PG8_LAS unsigned*)(lds + (bufoff) + ldsw + _i * 8192), 16, 0, 0); } while (0)
; #define PG8_WAIT_V(n) asm volatile("s_waitcnt vmcnt(" #n ")" ::: "memory")
; #define PG8_BAR __builtin_amdgcn_s_barrier()
; template <class Epi, class Sched, bool ALIGN_EPI = false, bool SP2 = false>
; __device__ __forceinline__ void gemm_phase(PG8_LAS unsigned char* lds, const Gemm g, const Sched& S, const Epi& E) {
;     ...
;     const unsigned ldsw = (unsigned)wid * 1024u;
;     const int aoff = lds_byte(wr * 64 + fr, fq * 8), boff = lds_byte(wc * 32 + fr, fq * 8);
;     ...
;         PG8_WAIT_V(2); PG8_BAR;
;         PG8_STAGE(PG8_SB(1, 0), cB + kstep, voffB); PG8_STAGE(PG8_SA(1, 0), cA + kstep, voffA); PG8_STAGE(PG8_SB(1, 1), cB + hstep + kstep, voffB);
;         PG8_WAIT_V(6); PG8_BAR;
.LBB0_1558:
	s_lshl_b32 s1, s1, 5
	s_mov_b64 s[14:15], 0x80
	s_and_b32 s1, s1, 0x60
	s_add_i32 m0, s27, 0x18000
	v_lshl_add_u64 v[6:7], v[6:7], 0, s[14:15]
	s_lshl_b32 s5, s0, 13
	s_lshl_b32 s6, s1, 7
	global_load_lds_dwordx4 v[6:7], off
	v_lshl_add_u64 v[4:5], v[4:5], 0, s[14:15]
	s_add_i32 m0, s27, 0x1a000
	s_add_i32 s34, s27, 0x8000
	s_add_i32 s35, s27, 0xa000
	global_load_lds_dwordx4 v[4:5], off
	v_lshl_add_u64 v[0:1], v[0:1], 0, s[14:15]
	s_mov_b32 m0, s34
	s_add_u32 s2, s22, 0xb0080
	global_load_lds_dwordx4 v[0:1], off
	v_lshl_add_u64 v[0:1], v[2:3], 0, s[14:15]
	s_mov_b32 m0, s35
	s_addc_u32 s3, s23, 0
	global_load_lds_dwordx4 v[0:1], off
	s_add_i32 m0, s27, 0x1c000
	v_lshl_add_u64 v[0:1], s[2:3], 0, v[128:129]
	global_load_lds_dwordx4 v[0:1], off
	v_lshl_add_u64 v[0:1], s[2:3], 0, v[130:131]
	s_add_i32 m0, s27, 0x1e000
	v_lshlrev_b32_e32 v3, 2, v150
	global_load_lds_dwordx4 v[0:1], off
	s_waitcnt vmcnt(8)
	s_barrier
	v_bfe_u32 v1, v150, 4, 2
	v_and_b32_e32 v0, 15, v150
	v_lshlrev_b32_e32 v2, 4, v1
	v_lshl_or_b32 v149, s0, 6, v0
	v_lshl_or_b32 v0, v0, 6, v2
	v_and_b32_e32 v3, 32, v3
	v_lshlrev_b32_e32 v4, 6, v150
	s_movk_i32 s0, 0x3c0
	v_bitop3_b32 v0, v0, s5, v3 bitop3:0xde
	v_and_or_b32 v2, v4, s0, v2
	s_waitcnt vmcnt(6)
	s_cmpk_lt_u32 s4, 0x100
	v_bitop3_b32 v151, s6, v2, v3 bitop3:0xf6
	s_cselect_b64 s[16:17], -1, 0
	s_add_i32 s38, 0, 0x10000
	s_add_i32 s39, 0, 0x14000
	v_add_u32_e32 v191, 0, v0
	v_mbcnt_lo_u32_b32 v0, -1, 0
	v_cmp_eq_u32_e64 s[2:3], 0, v1
	v_cmp_eq_u32_e64 s[4:5], 0, v148
	s_ashr_i32 s36, s89, 31
	s_ashr_i32 s37, s33, 31
	v_lshl_or_b32 v188, v1, 2, s1
	v_add3_u32 v132, v10, v8, v9
	v_mov_b32_e32 v133, v129
	v_add3_u32 v134, v11, v8, v9
	v_mov_b32_e32 v135, v129
	v_mov_b64_e32 v[136:137], 0x100
	v_mov_b64_e32 v[138:139], 0xff
	v_add_u32_e32 v189, s38, v151
	v_add_u32_e32 v190, s39, v151
	v_mbcnt_hi_u32_b32 v192, -1, v0
	v_mov_b32_e32 v193, 0x358637bd
	s_mov_b32 s40, 0x800000
	s_barrier
	s_branch .LBB0_1561

; DI unsigned pk2(float lo, float hi) { f32x2_t v = {lo, hi}; bf16x2_t b = __builtin_convertvector(v, bf16x2_t); return __builtin_bit_cast(unsigned, b); }
; DI float bf_lo(unsigned w) { return __uint_as_float(w << 16); }
; DI float bf_hi(unsigned w) { return __uint_as_float(w & 0xffff0000u); }
;     DI f32x4 base4(int row, int col) const {
;     ...
;         const u32x2 w = *(const u32x2*)(XB + (size_t)row * DM + col); return (f32x4){bf_lo(w.x), bf_hi(w.x), bf_lo(w.y), bf_hi(w.y)};
;     }
;     DI void operator()(AccRef acc, const Unit& u, int wr, int wc, int fr, int fq) const {
;         const int row0 = rowoff + u.pm * BM + wr * 64 + fr, col0 = u.pn * BM + wc * 32 + 4 * fq;
; #pragma unroll
;         for (int ai = 0; ai < 2; ++ai)
; #pragma unroll
;             for (int m = 0; m < 4; ++m) {
;                 const int row = row0 + ai * HALF + m * 16; float ss = 0.f;
; #pragma unroll
;                 for (int bj = 0; bj < 2; ++bj)
; #pragma unroll
;                     for (int n = 0; n < 2; ++n) {
;                         const int col = col0 + bj * HALF + n * 16;
;                         const f32x4 x = base4(row, col) + acc[ai][bj][m][n];
;                         ss += (x[0] * x[0] + x[1] * x[1]) + (x[2] * x[2] + x[3] * x[3]);
;                         if (FIRST && !dry) { u32x2 w; w.x = pk2(x[0], x[1]); w.y = pk2(x[2], x[3]); *(u32x2*)(XB + (size_t)row * DM + col) = w; }
;                     }
;                 ss += __shfl_xor(ss, 16); ss += __shfl_xor(ss, 32);
;                 if (fq == 0 && !dry) unsafeAtomicAdd(SS + row, ss);
.LBB0_1575:
	s_lshl_b32 s20, s43, 8
	s_lshl_b32 s21, s20, 11
	s_lshl_b32 s98, s44, 9
	s_add_u32 s21, s21, s98
	v_lshlrev_b32_e32 v228, 11, v149
	v_lshl_add_u32 v228, v188, 1, v228
	v_add_u32_e32 v228, s21, v228
	s_lshl_b32 s21, s20, 2
	v_lshlrev_b32_e32 v229, 2, v149
	v_add_u32_e32 v229, s21, v229
	s_lshl_b32 s21, s20, 12
	s_lshl_b32 s98, s44, 10
	s_add_u32 s21, s21, s98
	v_lshlrev_b32_e32 v230, 12, v149
	v_lshl_add_u32 v230, v188, 2, v230
	v_add_u32_e32 v230, s21, v230
	v_lshlrev_b32_e32 v231, 2, v188
	v_add_u32_e32 v231, s98, v231
	v_xor_b32_e32 v232, 16, v192
	v_lshlrev_b32_e32 v232, 2, v232
	v_xor_b32_e32 v233, 32, v192
	v_lshlrev_b32_e32 v233, 2, v233
	global_load_dwordx2 v[152:153], v228, s[92:93]
	global_load_dwordx2 v[154:155], v228, s[92:93] offset:32
	global_load_dwordx2 v[156:157], v228, s[92:93] offset:256
	global_load_dwordx2 v[158:159], v228, s[92:93] offset:288
	v_add_u32_e32 v228, 0x8000, v228
	global_load_dwordx2 v[160:161], v228, s[92:93]
	global_load_dwordx2 v[162:163], v228, s[92:93] offset:32
	global_load_dwordx2 v[164:165], v228, s[92:93] offset:256
	global_load_dwordx2 v[166:167], v228, s[92:93] offset:288
	v_add_u32_e32 v228, 0x8000, v228
	global_load_dwordx2 v[168:169], v228, s[92:93]
	global_load_dwordx2 v[170:171], v228, s[92:93] offset:32
	global_load_dwordx2 v[172:173], v228, s[92:93] offset:256
	global_load_dwordx2 v[174:175], v228, s[92:93] offset:288
	v_add_u32_e32 v228, 0x8000, v228
	global_load_dwordx2 v[176:177], v228, s[92:93]
	global_load_dwordx2 v[178:179], v228, s[92:93] offset:32
	global_load_dwordx2 v[180:181], v228, s[92:93] offset:256
	global_load_dwordx2 v[182:183], v228, s[92:93] offset:288
	v_add_u32_e32 v228, 0x28000, v228
	global_load_dwordx2 v[184:185], v228, s[92:93]
	global_load_dwordx2 v[186:187], v228, s[92:93] offset:32
	global_load_dwordx2 v[200:201], v228, s[92:93] offset:256
	global_load_dwordx2 v[202:203], v228, s[92:93] offset:288
	v_add_u32_e32 v228, 0x8000, v228
	global_load_dwordx2 v[204:205], v228, s[92:93]
	global_load_dwordx2 v[206:207], v228, s[92:93] offset:32
	global_load_dwordx2 v[208:209], v228, s[92:93] offset:256
	global_load_dwordx2 v[210:211], v228, s[92:93] offset:288
	v_add_u32_e32 v228, 0x8000, v228
	global_load_dwordx2 v[212:213], v228, s[92:93]
	global_load_dwordx2 v[214:215], v228, s[92:93] offset:32
	global_load_dwordx2 v[216:217], v228, s[92:93] offset:256
	global_load_dwordx2 v[218:219], v228, s[92:93] offset:288
	v_add_u32_e32 v228, 0x8000, v228
	global_load_dwordx2 v[220:221], v228, s[92:93]
	global_load_dwordx2 v[222:223], v228, s[92:93] offset:32
	global_load_dwordx2 v[224:225], v228, s[92:93] offset:256
	global_load_dwordx2 v[226:227], v228, s[92:93] offset:288
	s_waitcnt vmcnt(28)
	v_lshlrev_b32_e32 v140, 16, v152
	v_and_b32_e32 v141, 0xffff0000, v152
	v_lshlrev_b32_e32 v142, 16, v153
	v_and_b32_e32 v143, 0xffff0000, v153
	v_pk_add_f32 v[126:127], v[126:127], v[142:143]
	v_pk_add_f32 v[124:125], v[124:125], v[140:141]
	v_mul_f32_e32 v144, v125, v125
	v_mul_f32_e32 v145, v127, v127
	v_fmac_f32_e32 v144, v124, v124
	v_fmac_f32_e32 v145, v126, v126
	v_add_f32_e32 v146, v144, v145
	v_lshlrev_b32_e32 v140, 16, v154
	v_and_b32_e32 v141, 0xffff0000, v154
	v_lshlrev_b32_e32 v142, 16, v155
	v_and_b32_e32 v143, 0xffff0000, v155
	v_pk_add_f32 v[122:123], v[122:123], v[142:143]
	v_pk_add_f32 v[120:121], v[120:121], v[140:141]
	v_mul_f32_e32 v144, v121, v121
	v_mul_f32_e32 v145, v123, v123
	v_fmac_f32_e32 v144, v120, v120
	v_fmac_f32_e32 v145, v122, v122
	v_add_f32_e32 v144, v144, v145
	v_add_f32_e32 v146, v146, v144
	v_lshlrev_b32_e32 v140, 16, v156
	v_and_b32_e32 v141, 0xffff0000, v156
	v_lshlrev_b32_e32 v142, 16, v157
	v_and_b32_e32 v143, 0xffff0000, v157
	v_pk_add_f32 v[118:119], v[118:119], v[142:143]
	v_pk_add_f32 v[116:117], v[116:117], v[140:141]
	v_mul_f32_e32 v144, v117, v117
	v_mul_f32_e32 v145, v119, v119
	v_fmac_f32_e32 v144, v116, v116
	v_fmac_f32_e32 v145, v118, v118
	v_add_f32_e32 v144, v144, v145
	v_add_f32_e32 v146, v146, v144
	v_lshlrev_b32_e32 v140, 16, v158
	v_and_b32_e32 v141, 0xffff0000, v158
	v_lshlrev_b32_e32 v142, 16, v159
	v_and_b32_e32 v143, 0xffff0000, v159
	v_pk_add_f32 v[114:115], v[114:115], v[142:143]
	v_pk_add_f32 v[112:113], v[112:113], v[140:141]
	v_mul_f32_e32 v144, v113, v113
	v_mul_f32_e32 v145, v115, v115
	v_fmac_f32_e32 v144, v112, v112
	v_fmac_f32_e32 v145, v114, v114
	v_add_f32_e32 v144, v144, v145
	v_add_f32_e32 v146, v146, v144
	ds_bpermute_b32 v147, v232, v146
	s_waitcnt lgkmcnt(0)
	v_add_f32_e32 v146, v146, v147
	ds_bpermute_b32 v147, v233, v146
	s_waitcnt lgkmcnt(0)
	v_add_f32_e32 v146, v146, v147
	s_and_saveexec_b64 s[20:21], s[2:3]
	global_atomic_add_f32 v229, v146, s[12:13]
	s_or_b64 exec, exec, s[20:21]
	s_waitcnt vmcnt(25)
	v_lshlrev_b32_e32 v140, 16, v160
	v_and_b32_e32 v141, 0xffff0000, v160
	v_lshlrev_b32_e32 v142, 16, v161
	v_and_b32_e32 v143, 0xffff0000, v161
	v_pk_add_f32 v[110:111], v[110:111], v[142:143]
	v_pk_add_f32 v[108:109], v[108:109], v[140:141]
	v_mul_f32_e32 v144, v109, v109
	v_mul_f32_e32 v145, v111, v111
	v_fmac_f32_e32 v144, v108, v108
	v_fmac_f32_e32 v145, v110, v110
	v_add_f32_e32 v146, v144, v145
	v_lshlrev_b32_e32 v140, 16, v162
	v_and_b32_e32 v141, 0xffff0000, v162
	v_lshlrev_b32_e32 v142, 16, v163
	v_and_b32_e32 v143, 0xffff0000, v163
	v_pk_add_f32 v[106:107], v[106:107], v[142:143]
	v_pk_add_f32 v[104:105], v[104:105], v[140:141]
	v_mul_f32_e32 v144, v105, v105
	v_mul_f32_e32 v145, v107, v107
	v_fmac_f32_e32 v144, v104, v104
	v_fmac_f32_e32 v145, v106, v106
	v_add_f32_e32 v144, v144, v145
	v_add_f32_e32 v146, v146, v144
	v_lshlrev_b32_e32 v140, 16, v164
	v_and_b32_e32 v141, 0xffff0000, v164
	v_lshlrev_b32_e32 v142, 16, v165
	v_and_b32_e32 v143, 0xffff0000, v165
	v_pk_add_f32 v[102:103], v[102:103], v[142:143]
	v_pk_add_f32 v[100:101], v[100:101], v[140:141]
	v_mul_f32_e32 v144, v101, v101
	v_mul_f32_e32 v145, v103, v103
	v_fmac_f32_e32 v144, v100, v100
	v_fmac_f32_e32 v145, v102, v102
	v_add_f32_e32 v144, v144, v145
	v_add_f32_e32 v146, v146, v144
	v_lshlrev_b32_e32 v140, 16, v166
	v_and_b32_e32 v141, 0xffff0000, v166
	v_lshlrev_b32_e32 v142, 16, v167
	v_and_b32_e32 v143, 0xffff0000, v167
	v_pk_add_f32 v[98:99], v[98:99], v[142:143]
	v_pk_add_f32 v[96:97], v[96:97], v[140:141]
	v_mul_f32_e32 v144, v97, v97
	v_mul_f32_e32 v145, v99, v99
	v_fmac_f32_e32 v144, v96, v96
	v_fmac_f32_e32 v145, v98, v98
	v_add_f32_e32 v144, v144, v145
	v_add_f32_e32 v146, v146, v144
	ds_bpermute_b32 v147, v232, v146
	s_waitcnt lgkmcnt(0)
; DI unsigned pk2(float lo, float hi) { f32x2_t v = {lo, hi}; bf16x2_t b = __builtin_convertvector(v, bf16x2_t); return __builtin_bit_cast(unsigned, b); }
;     DI void operator()(AccRef acc, const Unit& u, int wr, int wc, int fr, int fq) const {
;     ...
;                 const int row = row0 + ai * HALF + m * 16; float ss = 0.f;
; #pragma unroll
;                 for (int bj = 0; bj < 2; ++bj)
; #pragma unroll
;                     for (int n = 0; n < 2; ++n) {
;                         const int col = col0 + bj * HALF + n * 16;
;                         const f32x4 x = base4(row, col) + acc[ai][bj][m][n];
;                         ss += (x[0] * x[0] + x[1] * x[1]) + (x[2] * x[2] + x[3] * x[3]);
;                         if (FIRST && !dry) { u32x2 w; w.x = pk2(x[0], x[1]); w.y = pk2(x[2], x[3]); *(u32x2*)(XB + (size_t)row * DM + col) = w; }
;                     }
;                 ss += __shfl_xor(ss, 16); ss += __shfl_xor(ss, 32);
;                 if (fq == 0 && !dry) unsafeAtomicAdd(SS + row, ss);
	v_add_f32_e32 v146, v146, v147
	ds_bpermute_b32 v147, v233, v146
	s_waitcnt lgkmcnt(0)
	v_add_f32_e32 v146, v146, v147
	s_and_saveexec_b64 s[20:21], s[2:3]
	global_atomic_add_f32 v229, v146, s[12:13] offset:64
	s_or_b64 exec, exec, s[20:21]
	s_waitcnt vmcnt(22)
	v_lshlrev_b32_e32 v140, 16, v168
	v_and_b32_e32 v141, 0xffff0000, v168
	v_lshlrev_b32_e32 v142, 16, v169
	v_and_b32_e32 v143, 0xffff0000, v169
	v_pk_add_f32 v[94:95], v[94:95], v[142:143]
	v_pk_add_f32 v[92:93], v[92:93], v[140:141]
	v_mul_f32_e32 v144, v93, v93
	v_mul_f32_e32 v145, v95, v95
	v_fmac_f32_e32 v144, v92, v92
	v_fmac_f32_e32 v145, v94, v94
	v_add_f32_e32 v146, v144, v145
	v_lshlrev_b32_e32 v140, 16, v170
	v_and_b32_e32 v141, 0xffff0000, v170
	v_lshlrev_b32_e32 v142, 16, v171
	v_and_b32_e32 v143, 0xffff0000, v171
	v_pk_add_f32 v[90:91], v[90:91], v[142:143]
	v_pk_add_f32 v[88:89], v[88:89], v[140:141]
	v_mul_f32_e32 v144, v89, v89
	v_mul_f32_e32 v145, v91, v91
	v_fmac_f32_e32 v144, v88, v88
	v_fmac_f32_e32 v145, v90, v90
	v_add_f32_e32 v144, v144, v145
	v_add_f32_e32 v146, v146, v144
	v_lshlrev_b32_e32 v140, 16, v172
	v_and_b32_e32 v141, 0xffff0000, v172
	v_lshlrev_b32_e32 v142, 16, v173
	v_and_b32_e32 v143, 0xffff0000, v173
	v_pk_add_f32 v[86:87], v[86:87], v[142:143]
	v_pk_add_f32 v[84:85], v[84:85], v[140:141]
	v_mul_f32_e32 v144, v85, v85
	v_mul_f32_e32 v145, v87, v87
	v_fmac_f32_e32 v144, v84, v84
	v_fmac_f32_e32 v145, v86, v86
	v_add_f32_e32 v144, v144, v145
	v_add_f32_e32 v146, v146, v144
	v_lshlrev_b32_e32 v140, 16, v174
	v_and_b32_e32 v141, 0xffff0000, v174
	v_lshlrev_b32_e32 v142, 16, v175
	v_and_b32_e32 v143, 0xffff0000, v175
	v_pk_add_f32 v[82:83], v[82:83], v[142:143]
	v_pk_add_f32 v[80:81], v[80:81], v[140:141]
	v_mul_f32_e32 v144, v81, v81
	v_mul_f32_e32 v145, v83, v83
	v_fmac_f32_e32 v144, v80, v80
	v_fmac_f32_e32 v145, v82, v82
	v_add_f32_e32 v144, v144, v145
	v_add_f32_e32 v146, v146, v144
	ds_bpermute_b32 v147, v232, v146
	s_waitcnt lgkmcnt(0)
	v_add_f32_e32 v146, v146, v147
	ds_bpermute_b32 v147, v233, v146
	s_waitcnt lgkmcnt(0)
	v_add_f32_e32 v146, v146, v147
	s_and_saveexec_b64 s[20:21], s[2:3]
	global_atomic_add_f32 v229, v146, s[12:13] offset:128
	s_or_b64 exec, exec, s[20:21]
	s_waitcnt vmcnt(19)
	v_lshlrev_b32_e32 v140, 16, v176
	v_and_b32_e32 v141, 0xffff0000, v176
	v_lshlrev_b32_e32 v142, 16, v177
	v_and_b32_e32 v143, 0xffff0000, v177
	v_pk_add_f32 v[78:79], v[78:79], v[142:143]
	v_pk_add_f32 v[76:77], v[76:77], v[140:141]
	v_mul_f32_e32 v144, v77, v77
	v_mul_f32_e32 v145, v79, v79
	v_fmac_f32_e32 v144, v76, v76
	v_fmac_f32_e32 v145, v78, v78
	v_add_f32_e32 v146, v144, v145
	v_lshlrev_b32_e32 v140, 16, v178
	v_and_b32_e32 v141, 0xffff0000, v178
	v_lshlrev_b32_e32 v142, 16, v179
	v_and_b32_e32 v143, 0xffff0000, v179
	v_pk_add_f32 v[74:75], v[74:75], v[142:143]
	v_pk_add_f32 v[72:73], v[72:73], v[140:141]
	v_mul_f32_e32 v144, v73, v73
	v_mul_f32_e32 v145, v75, v75
	v_fmac_f32_e32 v144, v72, v72
	v_fmac_f32_e32 v145, v74, v74
	v_add_f32_e32 v144, v144, v145
	v_add_f32_e32 v146, v146, v144
	v_lshlrev_b32_e32 v140, 16, v180
	v_and_b32_e32 v141, 0xffff0000, v180
	v_lshlrev_b32_e32 v142, 16, v181
	v_and_b32_e32 v143, 0xffff0000, v181
	v_pk_add_f32 v[70:71], v[70:71], v[142:143]
	v_pk_add_f32 v[68:69], v[68:69], v[140:141]
	v_mul_f32_e32 v144, v69, v69
	v_mul_f32_e32 v145, v71, v71
	v_fmac_f32_e32 v144, v68, v68
	v_fmac_f32_e32 v145, v70, v70
	v_add_f32_e32 v144, v144, v145
	v_add_f32_e32 v146, v146, v144
	v_lshlrev_b32_e32 v140, 16, v182
	v_and_b32_e32 v141, 0xffff0000, v182
	v_lshlrev_b32_e32 v142, 16, v183
	v_and_b32_e32 v143, 0xffff0000, v183
	v_pk_add_f32 v[66:67], v[66:67], v[142:143]
	v_pk_add_f32 v[64:65], v[64:65], v[140:141]
	v_mul_f32_e32 v144, v65, v65
	v_mul_f32_e32 v145, v67, v67
	v_fmac_f32_e32 v144, v64, v64
	v_fmac_f32_e32 v145, v66, v66
	v_add_f32_e32 v144, v144, v145
	v_add_f32_e32 v146, v146, v144
	ds_bpermute_b32 v147, v232, v146
	s_waitcnt lgkmcnt(0)
	v_add_f32_e32 v146, v146, v147
	ds_bpermute_b32 v147, v233, v146
	s_waitcnt lgkmcnt(0)
	v_add_f32_e32 v146, v146, v147
	s_and_saveexec_b64 s[20:21], s[2:3]
	global_atomic_add_f32 v229, v146, s[12:13] offset:192
	s_or_b64 exec, exec, s[20:21]
	s_waitcnt vmcnt(16)
	v_lshlrev_b32_e32 v140, 16, v184
	v_and_b32_e32 v141, 0xffff0000, v184
	v_lshlrev_b32_e32 v142, 16, v185
	v_and_b32_e32 v143, 0xffff0000, v185
	v_pk_add_f32 v[62:63], v[62:63], v[142:143]
	v_pk_add_f32 v[60:61], v[60:61], v[140:141]
	v_mul_f32_e32 v144, v61, v61
	v_mul_f32_e32 v145, v63, v63
	v_fmac_f32_e32 v144, v60, v60
	v_fmac_f32_e32 v145, v62, v62
	v_add_f32_e32 v146, v144, v145
	v_lshlrev_b32_e32 v140, 16, v186
	v_and_b32_e32 v141, 0xffff0000, v186
	v_lshlrev_b32_e32 v142, 16, v187
	v_and_b32_e32 v143, 0xffff0000, v187
	v_pk_add_f32 v[58:59], v[58:59], v[142:143]
	v_pk_add_f32 v[56:57], v[56:57], v[140:141]
	v_mul_f32_e32 v144, v57, v57
	v_mul_f32_e32 v145, v59, v59
	v_fmac_f32_e32 v144, v56, v56
	v_fmac_f32_e32 v145, v58, v58
	v_add_f32_e32 v144, v144, v145
	v_add_f32_e32 v146, v146, v144
	v_lshlrev_b32_e32 v140, 16, v200
	v_and_b32_e32 v141, 0xffff0000, v200
	v_lshlrev_b32_e32 v142, 16, v201
	v_and_b32_e32 v143, 0xffff0000, v201
	v_pk_add_f32 v[54:55], v[54:55], v[142:143]
	v_pk_add_f32 v[52:53], v[52:53], v[140:141]
	v_mul_f32_e32 v144, v53, v53
	v_mul_f32_e32 v145, v55, v55
	v_fmac_f32_e32 v144, v52, v52
	v_fmac_f32_e32 v145, v54, v54
	v_add_f32_e32 v144, v144, v145
	v_add_f32_e32 v146, v146, v144
	v_lshlrev_b32_e32 v140, 16, v202
	v_and_b32_e32 v141, 0xffff0000, v202
	v_lshlrev_b32_e32 v142, 16, v203
	v_and_b32_e32 v143, 0xffff0000, v203
	v_pk_add_f32 v[50:51], v[50:51], v[142:143]
	v_pk_add_f32 v[48:49], v[48:49], v[140:141]
	v_mul_f32_e32 v144, v49, v49
	v_mul_f32_e32 v145, v51, v51
	v_fmac_f32_e32 v144, v48, v48
	v_fmac_f32_e32 v145, v50, v50
	v_add_f32_e32 v144, v144, v145
	v_add_f32_e32 v146, v146, v144
	ds_bpermute_b32 v147, v232, v146
	s_waitcnt lgkmcnt(0)
; DI unsigned pk2(float lo, float hi) { f32x2_t v = {lo, hi}; bf16x2_t b = __builtin_convertvector(v, bf16x2_t); return __builtin_bit_cast(unsigned, b); }
;     DI void operator()(AccRef acc, const Unit& u, int wr, int wc, int fr, int fq) const {
;     ...
;                 const int row = row0 + ai * HALF + m * 16; float ss = 0.f;
; #pragma unroll
;                 for (int bj = 0; bj < 2; ++bj)
; #pragma unroll
;                     for (int n = 0; n < 2; ++n) {
;                         const int col = col0 + bj * HALF + n * 16;
;                         const f32x4 x = base4(row, col) + acc[ai][bj][m][n];
;                         ss += (x[0] * x[0] + x[1] * x[1]) + (x[2] * x[2] + x[3] * x[3]);
;                         if (FIRST && !dry) { u32x2 w; w.x = pk2(x[0], x[1]); w.y = pk2(x[2], x[3]); *(u32x2*)(XB + (size_t)row * DM + col) = w; }
;                     }
;                 ss += __shfl_xor(ss, 16); ss += __shfl_xor(ss, 32);
;                 if (fq == 0 && !dry) unsafeAtomicAdd(SS + row, ss);
;             }
;         if (FUSE) {
;             unsigned* pc = cnt + 16 * ((rowoff >> 8) + u.pm);
;             asm volatile("s_waitcnt vmcnt(0)" ::: "memory");
;             if ((threadIdx.x & 63) == 0) __hip_atomic_fetch_add(pc, 1u, __ATOMIC_RELAXED, __HIP_MEMORY_SCOPE_AGENT);
	v_add_f32_e32 v146, v146, v147
	ds_bpermute_b32 v147, v233, v146
	s_waitcnt lgkmcnt(0)
	v_add_f32_e32 v146, v146, v147
	s_and_saveexec_b64 s[20:21], s[2:3]
	global_atomic_add_f32 v229, v146, s[12:13] offset:512
	s_or_b64 exec, exec, s[20:21]
	s_waitcnt vmcnt(13)
	v_lshlrev_b32_e32 v140, 16, v204
	v_and_b32_e32 v141, 0xffff0000, v204
	v_lshlrev_b32_e32 v142, 16, v205
	v_and_b32_e32 v143, 0xffff0000, v205
	v_pk_add_f32 v[46:47], v[46:47], v[142:143]
	v_pk_add_f32 v[44:45], v[44:45], v[140:141]
	v_mul_f32_e32 v144, v45, v45
	v_mul_f32_e32 v145, v47, v47
	v_fmac_f32_e32 v144, v44, v44
	v_fmac_f32_e32 v145, v46, v46
	v_add_f32_e32 v146, v144, v145
	v_lshlrev_b32_e32 v140, 16, v206
	v_and_b32_e32 v141, 0xffff0000, v206
	v_lshlrev_b32_e32 v142, 16, v207
	v_and_b32_e32 v143, 0xffff0000, v207
	v_pk_add_f32 v[42:43], v[42:43], v[142:143]
	v_pk_add_f32 v[40:41], v[40:41], v[140:141]
	v_mul_f32_e32 v144, v41, v41
	v_mul_f32_e32 v145, v43, v43
	v_fmac_f32_e32 v144, v40, v40
	v_fmac_f32_e32 v145, v42, v42
	v_add_f32_e32 v144, v144, v145
	v_add_f32_e32 v146, v146, v144
	v_lshlrev_b32_e32 v140, 16, v208
	v_and_b32_e32 v141, 0xffff0000, v208
	v_lshlrev_b32_e32 v142, 16, v209
	v_and_b32_e32 v143, 0xffff0000, v209
	v_pk_add_f32 v[38:39], v[38:39], v[142:143]
	v_pk_add_f32 v[36:37], v[36:37], v[140:141]
	v_mul_f32_e32 v144, v37, v37
	v_mul_f32_e32 v145, v39, v39
	v_fmac_f32_e32 v144, v36, v36
	v_fmac_f32_e32 v145, v38, v38
	v_add_f32_e32 v144, v144, v145
	v_add_f32_e32 v146, v146, v144
	v_lshlrev_b32_e32 v140, 16, v210
	v_and_b32_e32 v141, 0xffff0000, v210
	v_lshlrev_b32_e32 v142, 16, v211
	v_and_b32_e32 v143, 0xffff0000, v211
	v_pk_add_f32 v[34:35], v[34:35], v[142:143]
	v_pk_add_f32 v[32:33], v[32:33], v[140:141]
	v_mul_f32_e32 v144, v33, v33
	v_mul_f32_e32 v145, v35, v35
	v_fmac_f32_e32 v144, v32, v32
	v_fmac_f32_e32 v145, v34, v34
	v_add_f32_e32 v144, v144, v145
	v_add_f32_e32 v146, v146, v144
	ds_bpermute_b32 v147, v232, v146
	s_waitcnt lgkmcnt(0)
	v_add_f32_e32 v146, v146, v147
	ds_bpermute_b32 v147, v233, v146
	s_waitcnt lgkmcnt(0)
	v_add_f32_e32 v146, v146, v147
	s_and_saveexec_b64 s[20:21], s[2:3]
	global_atomic_add_f32 v229, v146, s[12:13] offset:576
	s_or_b64 exec, exec, s[20:21]
	s_waitcnt vmcnt(10)
	v_lshlrev_b32_e32 v140, 16, v212
	v_and_b32_e32 v141, 0xffff0000, v212
	v_lshlrev_b32_e32 v142, 16, v213
	v_and_b32_e32 v143, 0xffff0000, v213
	v_pk_add_f32 v[30:31], v[30:31], v[142:143]
	v_pk_add_f32 v[28:29], v[28:29], v[140:141]
	v_mul_f32_e32 v144, v29, v29
	v_mul_f32_e32 v145, v31, v31
	v_fmac_f32_e32 v144, v28, v28
	v_fmac_f32_e32 v145, v30, v30
	v_add_f32_e32 v146, v144, v145
	v_lshlrev_b32_e32 v140, 16, v214
	v_and_b32_e32 v141, 0xffff0000, v214
	v_lshlrev_b32_e32 v142, 16, v215
	v_and_b32_e32 v143, 0xffff0000, v215
	v_pk_add_f32 v[26:27], v[26:27], v[142:143]
	v_pk_add_f32 v[24:25], v[24:25], v[140:141]
	v_mul_f32_e32 v144, v25, v25
	v_mul_f32_e32 v145, v27, v27
	v_fmac_f32_e32 v144, v24, v24
	v_fmac_f32_e32 v145, v26, v26
	v_add_f32_e32 v144, v144, v145
	v_add_f32_e32 v146, v146, v144
	v_lshlrev_b32_e32 v140, 16, v216
	v_and_b32_e32 v141, 0xffff0000, v216
	v_lshlrev_b32_e32 v142, 16, v217
	v_and_b32_e32 v143, 0xffff0000, v217
	v_pk_add_f32 v[22:23], v[22:23], v[142:143]
	v_pk_add_f32 v[20:21], v[20:21], v[140:141]
	v_mul_f32_e32 v144, v21, v21
	v_mul_f32_e32 v145, v23, v23
	v_fmac_f32_e32 v144, v20, v20
	v_fmac_f32_e32 v145, v22, v22
	v_add_f32_e32 v144, v144, v145
	v_add_f32_e32 v146, v146, v144
	v_lshlrev_b32_e32 v140, 16, v218
	v_and_b32_e32 v141, 0xffff0000, v218
	v_lshlrev_b32_e32 v142, 16, v219
	v_and_b32_e32 v143, 0xffff0000, v219
	v_pk_add_f32 v[18:19], v[18:19], v[142:143]
	v_pk_add_f32 v[16:17], v[16:17], v[140:141]
	v_mul_f32_e32 v144, v17, v17
	v_mul_f32_e32 v145, v19, v19
	v_fmac_f32_e32 v144, v16, v16
	v_fmac_f32_e32 v145, v18, v18
	v_add_f32_e32 v144, v144, v145
	v_add_f32_e32 v146, v146, v144
	ds_bpermute_b32 v147, v232, v146
	s_waitcnt lgkmcnt(0)
	v_add_f32_e32 v146, v146, v147
	ds_bpermute_b32 v147, v233, v146
	s_waitcnt lgkmcnt(0)
	v_add_f32_e32 v146, v146, v147
	s_and_saveexec_b64 s[20:21], s[2:3]
	global_atomic_add_f32 v229, v146, s[12:13] offset:640
	s_or_b64 exec, exec, s[20:21]
	s_waitcnt vmcnt(7)
	v_lshlrev_b32_e32 v140, 16, v220
	v_and_b32_e32 v141, 0xffff0000, v220
	v_lshlrev_b32_e32 v142, 16, v221
	v_and_b32_e32 v143, 0xffff0000, v221
	v_pk_add_f32 v[14:15], v[14:15], v[142:143]
	v_pk_add_f32 v[12:13], v[12:13], v[140:141]
	v_mul_f32_e32 v144, v13, v13
	v_mul_f32_e32 v145, v15, v15
	v_fmac_f32_e32 v144, v12, v12
	v_fmac_f32_e32 v145, v14, v14
	v_add_f32_e32 v146, v144, v145
	v_lshlrev_b32_e32 v140, 16, v222
	v_and_b32_e32 v141, 0xffff0000, v222
	v_lshlrev_b32_e32 v142, 16, v223
	v_and_b32_e32 v143, 0xffff0000, v223
	v_pk_add_f32 v[10:11], v[10:11], v[142:143]
	v_pk_add_f32 v[8:9], v[8:9], v[140:141]
	v_mul_f32_e32 v144, v9, v9
	v_mul_f32_e32 v145, v11, v11
	v_fmac_f32_e32 v144, v8, v8
	v_fmac_f32_e32 v145, v10, v10
	v_add_f32_e32 v144, v144, v145
	v_add_f32_e32 v146, v146, v144
	v_lshlrev_b32_e32 v140, 16, v224
	v_and_b32_e32 v141, 0xffff0000, v224
	v_lshlrev_b32_e32 v142, 16, v225
	v_and_b32_e32 v143, 0xffff0000, v225
	v_pk_add_f32 v[6:7], v[6:7], v[142:143]
	v_pk_add_f32 v[4:5], v[4:5], v[140:141]
	v_mul_f32_e32 v144, v5, v5
	v_mul_f32_e32 v145, v7, v7
	v_fmac_f32_e32 v144, v4, v4
	v_fmac_f32_e32 v145, v6, v6
	v_add_f32_e32 v144, v144, v145
	v_add_f32_e32 v146, v146, v144
	v_lshlrev_b32_e32 v140, 16, v226
	v_and_b32_e32 v141, 0xffff0000, v226
	v_lshlrev_b32_e32 v142, 16, v227
	v_and_b32_e32 v143, 0xffff0000, v227
	v_pk_add_f32 v[2:3], v[2:3], v[142:143]
	v_pk_add_f32 v[0:1], v[0:1], v[140:141]
	v_mul_f32_e32 v144, v1, v1
	v_mul_f32_e32 v145, v3, v3
	v_fmac_f32_e32 v144, v0, v0
	v_fmac_f32_e32 v145, v2, v2
	v_add_f32_e32 v144, v144, v145
	v_add_f32_e32 v146, v146, v144
	ds_bpermute_b32 v147, v232, v146
	s_waitcnt lgkmcnt(0)
	v_add_f32_e32 v146, v146, v147
	ds_bpermute_b32 v147, v233, v146
	s_waitcnt lgkmcnt(0)
	v_add_f32_e32 v146, v146, v147
	s_and_saveexec_b64 s[20:21], s[2:3]
	global_atomic_add_f32 v229, v146, s[12:13] offset:704
	s_or_b64 exec, exec, s[20:21]
	s_lshl_b32 s20, s43, 4
	s_ashr_i32 s21, s20, 31
	s_lshl_b64 s[20:21], s[20:21], 2
	s_waitcnt vmcnt(0)
	s_add_u32 s20, s60, s20
	s_addc_u32 s21, s61, s21
	s_and_saveexec_b64 s[22:23], s[4:5]
	s_cbranch_execz .LBB0_1594
	s_mov_b64 s[24:25], exec
	v_mbcnt_lo_u32_b32 v242, s24, 0
	v_mbcnt_hi_u32_b32 v242, s25, v242
	v_cmp_eq_u32_e32 vcc, 0, v242
	s_and_b64 s[44:45], exec, vcc
	s_mov_b64 exec, s[44:45]
	s_cbranch_execz .LBB0_1594
	s_bcnt1_i32_b64 s24, s[24:25]
	v_mov_b32_e32 v242, s24
	global_atomic_add v129, v242, s[20:21]
.LBB0_1594:
	s_or_b64 exec, exec, s[22:23]
	v_mov_b32_e32 v242, 0x400000
	s_branch .LBB0_1596

;     DI void operator()(AccRef acc, const Unit& u, int wr, int wc, int fr, int fq) const {
;     ...
;             unsigned spins = 0;
;             for (;;) { const unsigned v = __hip_atomic_load(pc, __ATOMIC_RELAXED, __HIP_MEMORY_SCOPE_AGENT);
;                 if ((unsigned)__builtin_amdgcn_readfirstlane(v) >= 32u || ++spins > (1u << 22)) break; __builtin_amdgcn_s_sleep(2); }
;             __builtin_amdgcn_fence(__ATOMIC_ACQUIRE, "agent");
; #pragma unroll
;             for (int ai = 0; ai < 2; ++ai)
; #pragma unroll
;                 for (int m = 0; m < 4; ++m) {
;                     const int row = row0 + ai * HALF + m * 16;
;                     const float rs = rsqrtf(__hip_atomic_load(SS + row, __ATOMIC_RELAXED, __HIP_MEMORY_SCOPE_AGENT) * (1.0f / DM) + EPSN);
; #pragma unroll
;                     for (int bj = 0; bj < 2; ++bj)
; #pragma unroll
;                         for (int n = 0; n < 2; ++n) {
;                             const int col = col0 + bj * HALF + n * 16;
;                             const f32x4 x = base4(row, col) + acc[ai][bj][m][n];
;                             if (!dry) *(f32x4*)(out + (size_t)row * DM + col) = x * rs * *(const f32x4*)(gain + col);
.LBB0_1596:
	s_waitcnt lgkmcnt(0)
	global_load_dword v243, v129, s[20:21] sc1
	v_subrev_co_u32_e32 v242, vcc, 1, v242
	s_waitcnt vmcnt(0)
	v_readfirstlane_b32 s22, v243
	s_cmp_gt_u32 s22, 31
	s_cselect_b64 s[22:23], -1, 0
	s_or_b64 s[22:23], s[22:23], vcc
	s_and_b64 vcc, exec, s[22:23]
	s_cbranch_vccz .LBB0_1595
.LBB0_1598:
	buffer_inv sc1
	global_load_dword v234, v229, s[12:13] sc1
	global_load_dword v235, v229, s[12:13] offset:64 sc1
	global_load_dword v236, v229, s[12:13] offset:128 sc1
	global_load_dword v237, v229, s[12:13] offset:192 sc1
	global_load_dword v238, v229, s[12:13] offset:512 sc1
	global_load_dword v239, v229, s[12:13] offset:576 sc1
	global_load_dword v240, v229, s[12:13] offset:640 sc1
	global_load_dword v241, v229, s[12:13] offset:704 sc1
	global_load_dwordx4 v[152:155], v231, s[62:63]
	global_load_dwordx4 v[156:159], v231, s[62:63] offset:64
	global_load_dwordx4 v[160:163], v231, s[62:63] offset:512
	global_load_dwordx4 v[164:167], v231, s[62:63] offset:576
	s_waitcnt vmcnt(0)
	v_fmamk_f32 v244, v234, 0x3a800000, v193
	v_mul_f32_e32 v140, 0x4b800000, v244
	v_cmp_gt_f32_e32 vcc, s40, v244
	s_nop 1
	v_cndmask_b32_e32 v244, v244, v140, vcc
	v_rsq_f32_e32 v244, v244
	s_nop 0
	v_mul_f32_e32 v140, 0x45800000, v244
	v_cndmask_b32_e32 v244, v244, v140, vcc
	v_pk_mul_f32 v[124:125], v[124:125], v[244:245] op_sel_hi:[1,0]
	v_pk_mul_f32 v[126:127], v[126:127], v[244:245] op_sel_hi:[1,0]
	v_pk_mul_f32 v[124:125], v[152:153], v[124:125]
	v_pk_mul_f32 v[126:127], v[154:155], v[126:127]
	global_store_dwordx4 v230, v[124:127], s[80:81]
	v_pk_mul_f32 v[120:121], v[120:121], v[244:245] op_sel_hi:[1,0]
	v_pk_mul_f32 v[122:123], v[122:123], v[244:245] op_sel_hi:[1,0]
	v_pk_mul_f32 v[120:121], v[156:157], v[120:121]
	v_pk_mul_f32 v[122:123], v[158:159], v[122:123]
	global_store_dwordx4 v230, v[120:123], s[80:81] offset:64
	v_pk_mul_f32 v[116:117], v[116:117], v[244:245] op_sel_hi:[1,0]
	v_pk_mul_f32 v[118:119], v[118:119], v[244:245] op_sel_hi:[1,0]
	v_pk_mul_f32 v[116:117], v[160:161], v[116:117]
	v_pk_mul_f32 v[118:119], v[162:163], v[118:119]
	global_store_dwordx4 v230, v[116:119], s[80:81] offset:512
	v_pk_mul_f32 v[112:113], v[112:113], v[244:245] op_sel_hi:[1,0]
	v_pk_mul_f32 v[114:115], v[114:115], v[244:245] op_sel_hi:[1,0]
	v_pk_mul_f32 v[112:113], v[164:165], v[112:113]
	v_pk_mul_f32 v[114:115], v[166:167], v[114:115]
	global_store_dwordx4 v230, v[112:115], s[80:81] offset:576
	v_add_u32_e32 v230, 0x10000, v230
	s_waitcnt vmcnt(14)
	v_fmamk_f32 v244, v235, 0x3a800000, v193
	v_mul_f32_e32 v140, 0x4b800000, v244
	v_cmp_gt_f32_e32 vcc, s40, v244
	s_nop 1
	v_cndmask_b32_e32 v244, v244, v140, vcc
	v_rsq_f32_e32 v244, v244
	s_nop 0
	v_mul_f32_e32 v140, 0x45800000, v244
	v_cndmask_b32_e32 v244, v244, v140, vcc
	v_pk_mul_f32 v[108:109], v[108:109], v[244:245] op_sel_hi:[1,0]
	v_pk_mul_f32 v[110:111], v[110:111], v[244:245] op_sel_hi:[1,0]
	v_pk_mul_f32 v[108:109], v[152:153], v[108:109]
	v_pk_mul_f32 v[110:111], v[154:155], v[110:111]
	global_store_dwordx4 v230, v[108:111], s[80:81]
	v_pk_mul_f32 v[104:105], v[104:105], v[244:245] op_sel_hi:[1,0]
	v_pk_mul_f32 v[106:107], v[106:107], v[244:245] op_sel_hi:[1,0]
	v_pk_mul_f32 v[104:105], v[156:157], v[104:105]
	v_pk_mul_f32 v[106:107], v[158:159], v[106:107]
	global_store_dwordx4 v230, v[104:107], s[80:81] offset:64
	v_pk_mul_f32 v[100:101], v[100:101], v[244:245] op_sel_hi:[1,0]
	v_pk_mul_f32 v[102:103], v[102:103], v[244:245] op_sel_hi:[1,0]
	v_pk_mul_f32 v[100:101], v[160:161], v[100:101]
	v_pk_mul_f32 v[102:103], v[162:163], v[102:103]
	global_store_dwordx4 v230, v[100:103], s[80:81] offset:512
	v_pk_mul_f32 v[96:97], v[96:97], v[244:245] op_sel_hi:[1,0]
	v_pk_mul_f32 v[98:99], v[98:99], v[244:245] op_sel_hi:[1,0]
	v_pk_mul_f32 v[96:97], v[164:165], v[96:97]
	v_pk_mul_f32 v[98:99], v[166:167], v[98:99]
	global_store_dwordx4 v230, v[96:99], s[80:81] offset:576
	v_add_u32_e32 v230, 0x10000, v230
	s_waitcnt vmcnt(17)
	v_fmamk_f32 v244, v236, 0x3a800000, v193
	v_mul_f32_e32 v140, 0x4b800000, v244
	v_cmp_gt_f32_e32 vcc, s40, v244
	s_nop 1
	v_cndmask_b32_e32 v244, v244, v140, vcc
	v_rsq_f32_e32 v244, v244
	s_nop 0
	v_mul_f32_e32 v140, 0x45800000, v244
	v_cndmask_b32_e32 v244, v244, v140, vcc
	v_pk_mul_f32 v[92:93], v[92:93], v[244:245] op_sel_hi:[1,0]
	v_pk_mul_f32 v[94:95], v[94:95], v[244:245] op_sel_hi:[1,0]
	v_pk_mul_f32 v[92:93], v[152:153], v[92:93]
	v_pk_mul_f32 v[94:95], v[154:155], v[94:95]
	global_store_dwordx4 v230, v[92:95], s[80:81]
	v_pk_mul_f32 v[88:89], v[88:89], v[244:245] op_sel_hi:[1,0]
	v_pk_mul_f32 v[90:91], v[90:91], v[244:245] op_sel_hi:[1,0]
	v_pk_mul_f32 v[88:89], v[156:157], v[88:89]
	v_pk_mul_f32 v[90:91], v[158:159], v[90:91]
	global_store_dwordx4 v230, v[88:91], s[80:81] offset:64
	v_pk_mul_f32 v[84:85], v[84:85], v[244:245] op_sel_hi:[1,0]
	v_pk_mul_f32 v[86:87], v[86:87], v[244:245] op_sel_hi:[1,0]
	v_pk_mul_f32 v[84:85], v[160:161], v[84:85]
	v_pk_mul_f32 v[86:87], v[162:163], v[86:87]
	global_store_dwordx4 v230, v[84:87], s[80:81] offset:512
	v_pk_mul_f32 v[80:81], v[80:81], v[244:245] op_sel_hi:[1,0]
	v_pk_mul_f32 v[82:83], v[82:83], v[244:245] op_sel_hi:[1,0]
	v_pk_mul_f32 v[80:81], v[164:165], v[80:81]
	v_pk_mul_f32 v[82:83], v[166:167], v[82:83]
	global_store_dwordx4 v230, v[80:83], s[80:81] offset:576
	v_add_u32_e32 v230, 0x10000, v230
	s_waitcnt vmcnt(20)
;     DI void operator()(AccRef acc, const Unit& u, int wr, int wc, int fr, int fq) const {
;     ...
; #pragma unroll
;             for (int ai = 0; ai < 2; ++ai)
; #pragma unroll
;                 for (int m = 0; m < 4; ++m) {
;                     const int row = row0 + ai * HALF + m * 16;
;                     const float rs = rsqrtf(__hip_atomic_load(SS + row, __ATOMIC_RELAXED, __HIP_MEMORY_SCOPE_AGENT) * (1.0f / DM) + EPSN);
; #pragma unroll
;                     for (int bj = 0; bj < 2; ++bj)
; #pragma unroll
;                         for (int n = 0; n < 2; ++n) {
;                             const int col = col0 + bj * HALF + n * 16;
;                             const f32x4 x = base4(row, col) + acc[ai][bj][m][n];
;                             if (!dry) *(f32x4*)(out + (size_t)row * DM + col) = x * rs * *(const f32x4*)(gain + col);
	v_fmamk_f32 v244, v237, 0x3a800000, v193
	v_mul_f32_e32 v140, 0x4b800000, v244
	v_cmp_gt_f32_e32 vcc, s40, v244
	s_nop 1
	v_cndmask_b32_e32 v244, v244, v140, vcc
	v_rsq_f32_e32 v244, v244
	s_nop 0
	v_mul_f32_e32 v140, 0x45800000, v244
	v_cndmask_b32_e32 v244, v244, v140, vcc
	v_pk_mul_f32 v[76:77], v[76:77], v[244:245] op_sel_hi:[1,0]
	v_pk_mul_f32 v[78:79], v[78:79], v[244:245] op_sel_hi:[1,0]
	v_pk_mul_f32 v[76:77], v[152:153], v[76:77]
	v_pk_mul_f32 v[78:79], v[154:155], v[78:79]
	global_store_dwordx4 v230, v[76:79], s[80:81]
	v_pk_mul_f32 v[72:73], v[72:73], v[244:245] op_sel_hi:[1,0]
	v_pk_mul_f32 v[74:75], v[74:75], v[244:245] op_sel_hi:[1,0]
	v_pk_mul_f32 v[72:73], v[156:157], v[72:73]
	v_pk_mul_f32 v[74:75], v[158:159], v[74:75]
	global_store_dwordx4 v230, v[72:75], s[80:81] offset:64
	v_pk_mul_f32 v[68:69], v[68:69], v[244:245] op_sel_hi:[1,0]
	v_pk_mul_f32 v[70:71], v[70:71], v[244:245] op_sel_hi:[1,0]
	v_pk_mul_f32 v[68:69], v[160:161], v[68:69]
	v_pk_mul_f32 v[70:71], v[162:163], v[70:71]
	global_store_dwordx4 v230, v[68:71], s[80:81] offset:512
	v_pk_mul_f32 v[64:65], v[64:65], v[244:245] op_sel_hi:[1,0]
	v_pk_mul_f32 v[66:67], v[66:67], v[244:245] op_sel_hi:[1,0]
	v_pk_mul_f32 v[64:65], v[164:165], v[64:65]
	v_pk_mul_f32 v[66:67], v[166:167], v[66:67]
	global_store_dwordx4 v230, v[64:67], s[80:81] offset:576
	v_add_u32_e32 v230, 0x50000, v230
	s_waitcnt vmcnt(23)
	v_fmamk_f32 v244, v238, 0x3a800000, v193
	v_mul_f32_e32 v140, 0x4b800000, v244
	v_cmp_gt_f32_e32 vcc, s40, v244
	s_nop 1
	v_cndmask_b32_e32 v244, v244, v140, vcc
	v_rsq_f32_e32 v244, v244
	s_nop 0
	v_mul_f32_e32 v140, 0x45800000, v244
	v_cndmask_b32_e32 v244, v244, v140, vcc
	v_pk_mul_f32 v[60:61], v[60:61], v[244:245] op_sel_hi:[1,0]
	v_pk_mul_f32 v[62:63], v[62:63], v[244:245] op_sel_hi:[1,0]
	v_pk_mul_f32 v[60:61], v[152:153], v[60:61]
	v_pk_mul_f32 v[62:63], v[154:155], v[62:63]
	global_store_dwordx4 v230, v[60:63], s[80:81]
	v_pk_mul_f32 v[56:57], v[56:57], v[244:245] op_sel_hi:[1,0]
	v_pk_mul_f32 v[58:59], v[58:59], v[244:245] op_sel_hi:[1,0]
	v_pk_mul_f32 v[56:57], v[156:157], v[56:57]
	v_pk_mul_f32 v[58:59], v[158:159], v[58:59]
	global_store_dwordx4 v230, v[56:59], s[80:81] offset:64
	v_pk_mul_f32 v[52:53], v[52:53], v[244:245] op_sel_hi:[1,0]
	v_pk_mul_f32 v[54:55], v[54:55], v[244:245] op_sel_hi:[1,0]
	v_pk_mul_f32 v[52:53], v[160:161], v[52:53]
	v_pk_mul_f32 v[54:55], v[162:163], v[54:55]
	global_store_dwordx4 v230, v[52:55], s[80:81] offset:512
	v_pk_mul_f32 v[48:49], v[48:49], v[244:245] op_sel_hi:[1,0]
	v_pk_mul_f32 v[50:51], v[50:51], v[244:245] op_sel_hi:[1,0]
	v_pk_mul_f32 v[48:49], v[164:165], v[48:49]
	v_pk_mul_f32 v[50:51], v[166:167], v[50:51]
	global_store_dwordx4 v230, v[48:51], s[80:81] offset:576
	v_add_u32_e32 v230, 0x10000, v230
	s_waitcnt vmcnt(26)
	v_fmamk_f32 v244, v239, 0x3a800000, v193
	v_mul_f32_e32 v140, 0x4b800000, v244
	v_cmp_gt_f32_e32 vcc, s40, v244
	s_nop 1
	v_cndmask_b32_e32 v244, v244, v140, vcc
	v_rsq_f32_e32 v244, v244
	s_nop 0
	v_mul_f32_e32 v140, 0x45800000, v244
	v_cndmask_b32_e32 v244, v244, v140, vcc
	v_pk_mul_f32 v[44:45], v[44:45], v[244:245] op_sel_hi:[1,0]
	v_pk_mul_f32 v[46:47], v[46:47], v[244:245] op_sel_hi:[1,0]
	v_pk_mul_f32 v[44:45], v[152:153], v[44:45]
	v_pk_mul_f32 v[46:47], v[154:155], v[46:47]
	global_store_dwordx4 v230, v[44:47], s[80:81]
	v_pk_mul_f32 v[40:41], v[40:41], v[244:245] op_sel_hi:[1,0]
	v_pk_mul_f32 v[42:43], v[42:43], v[244:245] op_sel_hi:[1,0]
	v_pk_mul_f32 v[40:41], v[156:157], v[40:41]
	v_pk_mul_f32 v[42:43], v[158:159], v[42:43]
	global_store_dwordx4 v230, v[40:43], s[80:81] offset:64
	v_pk_mul_f32 v[36:37], v[36:37], v[244:245] op_sel_hi:[1,0]
	v_pk_mul_f32 v[38:39], v[38:39], v[244:245] op_sel_hi:[1,0]
	v_pk_mul_f32 v[36:37], v[160:161], v[36:37]
	v_pk_mul_f32 v[38:39], v[162:163], v[38:39]
	global_store_dwordx4 v230, v[36:39], s[80:81] offset:512
	v_pk_mul_f32 v[32:33], v[32:33], v[244:245] op_sel_hi:[1,0]
	v_pk_mul_f32 v[34:35], v[34:35], v[244:245] op_sel_hi:[1,0]
	v_pk_mul_f32 v[32:33], v[164:165], v[32:33]
	v_pk_mul_f32 v[34:35], v[166:167], v[34:35]
	global_store_dwordx4 v230, v[32:35], s[80:81] offset:576
	v_add_u32_e32 v230, 0x10000, v230
	s_waitcnt vmcnt(29)
	v_fmamk_f32 v244, v240, 0x3a800000, v193
	v_mul_f32_e32 v140, 0x4b800000, v244
	v_cmp_gt_f32_e32 vcc, s40, v244
	s_nop 1
	v_cndmask_b32_e32 v244, v244, v140, vcc
	v_rsq_f32_e32 v244, v244
	s_nop 0
	v_mul_f32_e32 v140, 0x45800000, v244
	v_cndmask_b32_e32 v244, v244, v140, vcc
	v_pk_mul_f32 v[28:29], v[28:29], v[244:245] op_sel_hi:[1,0]
	v_pk_mul_f32 v[30:31], v[30:31], v[244:245] op_sel_hi:[1,0]
	v_pk_mul_f32 v[28:29], v[152:153], v[28:29]
	v_pk_mul_f32 v[30:31], v[154:155], v[30:31]
	global_store_dwordx4 v230, v[28:31], s[80:81]
	v_pk_mul_f32 v[24:25], v[24:25], v[244:245] op_sel_hi:[1,0]
	v_pk_mul_f32 v[26:27], v[26:27], v[244:245] op_sel_hi:[1,0]
	v_pk_mul_f32 v[24:25], v[156:157], v[24:25]
	v_pk_mul_f32 v[26:27], v[158:159], v[26:27]
	global_store_dwordx4 v230, v[24:27], s[80:81] offset:64
	v_pk_mul_f32 v[20:21], v[20:21], v[244:245] op_sel_hi:[1,0]
	v_pk_mul_f32 v[22:23], v[22:23], v[244:245] op_sel_hi:[1,0]
	v_pk_mul_f32 v[20:21], v[160:161], v[20:21]
	v_pk_mul_f32 v[22:23], v[162:163], v[22:23]
	global_store_dwordx4 v230, v[20:23], s[80:81] offset:512
	v_pk_mul_f32 v[16:17], v[16:17], v[244:245] op_sel_hi:[1,0]
	v_pk_mul_f32 v[18:19], v[18:19], v[244:245] op_sel_hi:[1,0]
	v_pk_mul_f32 v[16:17], v[164:165], v[16:17]
	v_pk_mul_f32 v[18:19], v[166:167], v[18:19]
	global_store_dwordx4 v230, v[16:19], s[80:81] offset:576
	v_add_u32_e32 v230, 0x10000, v230
	s_waitcnt vmcnt(32)
	v_fmamk_f32 v244, v241, 0x3a800000, v193
	v_mul_f32_e32 v140, 0x4b800000, v244
	v_cmp_gt_f32_e32 vcc, s40, v244
	s_nop 1
	v_cndmask_b32_e32 v244, v244, v140, vcc
	v_rsq_f32_e32 v244, v244
	s_nop 0
	v_mul_f32_e32 v140, 0x45800000, v244
	v_cndmask_b32_e32 v244, v244, v140, vcc
	v_pk_mul_f32 v[12:13], v[12:13], v[244:245] op_sel_hi:[1,0]
	v_pk_mul_f32 v[14:15], v[14:15], v[244:245] op_sel_hi:[1,0]
	v_pk_mul_f32 v[12:13], v[152:153], v[12:13]
	v_pk_mul_f32 v[14:15], v[154:155], v[14:15]
	global_store_dwordx4 v230, v[12:15], s[80:81]
	v_pk_mul_f32 v[8:9], v[8:9], v[244:245] op_sel_hi:[1,0]
	v_pk_mul_f32 v[10:11], v[10:11], v[244:245] op_sel_hi:[1,0]
	v_pk_mul_f32 v[8:9], v[156:157], v[8:9]
	v_pk_mul_f32 v[10:11], v[158:159], v[10:11]
	global_store_dwordx4 v230, v[8:11], s[80:81] offset:64
	v_pk_mul_f32 v[4:5], v[4:5], v[244:245] op_sel_hi:[1,0]
	v_pk_mul_f32 v[6:7], v[6:7], v[244:245] op_sel_hi:[1,0]
	v_pk_mul_f32 v[4:5], v[160:161], v[4:5]
	v_pk_mul_f32 v[6:7], v[162:163], v[6:7]
	global_store_dwordx4 v230, v[4:7], s[80:81] offset:512
	v_pk_mul_f32 v[0:1], v[0:1], v[244:245] op_sel_hi:[1,0]
	v_pk_mul_f32 v[2:3], v[2:3], v[244:245] op_sel_hi:[1,0]
	v_pk_mul_f32 v[0:1], v[164:165], v[0:1]
	v_pk_mul_f32 v[2:3], v[166:167], v[2:3]
	global_store_dwordx4 v230, v[0:3], s[80:81] offset:576
	s_and_b64 vcc, exec, s[6:7]
	s_mov_b64 s[6:7], -1
	s_cbranch_vccnz .LBB0_1560
; #define PG8_BAR __builtin_amdgcn_s_barrier()
; template <class Epi, class Sched, bool ALIGN_EPI = false, bool SP2 = false>
; __device__ __forceinline__ void gemm_phase(PG8_LAS unsigned char* lds, const Gemm g, const Sched& S, const Epi& E) {
;     ...
;         cur = nxt; cA = nA; cB = nB; ++ui;
;         if constexpr (ALIGN_EPI) { if (wr == 1) PG8_BAR; }
;     }
	s_andn2_b64 vcc, exec, s[10:11]
	s_cbranch_vccnz .LBB0_1559
	s_barrier
	s_branch .LBB0_1559

; #define PG8_STAGE(bufoff, gbase, voff) do { _Pragma("unroll") for (int _i = 0; _i < 2; ++_i) \
;         __builtin_amdgcn_global_load_lds((const unsigned*)((const char*)(gbase) + (voff)[_i]), (PG8_LAS unsigned*)(lds + (bufoff) + ldsw + _i * 8192), 16, 0, 0); } while (0)
; #define PG8_WAIT_V(n) asm volatile("s_waitcnt vmcnt(" #n ")" ::: "memory")
; #define PG8_BAR __builtin_amdgcn_s_barrier()
; template <class Epi, class Sched, bool ALIGN_EPI = false, bool SP2 = false>
; __device__ __forceinline__ void gemm_phase(PG8_LAS unsigned char* lds, const Gemm g, const Sched& S, const Epi& E) {
;     ...
;     if constexpr (SP2) {
;         PG8_STAGE(PG8_SB(0, 0), cB, voffB); PG8_STAGE(PG8_SB(0, 1), cB + hstep, voffB); PG8_STAGE(PG8_SA(0, 0), cA, voffA); PG8_STAGE(PG8_SA(0, 1), cA + hstep, voffA);
;         if (wr == 1) PG8_BAR;
;         PG8_WAIT_V(2); PG8_BAR;
;         PG8_STAGE(PG8_SB(1, 0), cB + kstep, voffB); PG8_STAGE(PG8_SA(1, 0), cA + kstep, voffA); PG8_STAGE(PG8_SB(1, 1), cB + hstep + kstep, voffB);
;         PG8_WAIT_V(6); PG8_BAR;
.LBB0_1660:
	s_add_u32 s18, s82, 0x30000
	s_addc_u32 s19, s83, 0
	s_lshl_b32 s1, s9, 5
	s_mov_b64 s[20:21], 0x80
	s_and_b32 s9, s1, 0x60
	s_add_i32 m0, s39, 0x18000
	v_lshl_add_u64 v[6:7], v[6:7], 0, s[20:21]
	s_lshl_b32 s22, s8, 13
	s_lshl_b32 s23, s9, 7
	global_load_lds_dwordx4 v[6:7], off
	v_lshl_add_u64 v[4:5], v[4:5], 0, s[20:21]
	s_add_i32 m0, s39, 0x1a000
	s_add_i32 s44, s39, 0x8000
	s_add_i32 s45, s39, 0xa000
	global_load_lds_dwordx4 v[4:5], off
	v_lshl_add_u64 v[0:1], v[0:1], 0, s[20:21]
	s_mov_b32 m0, s44
	s_add_u32 s10, s6, 0x40080
	global_load_lds_dwordx4 v[0:1], off
	v_lshl_add_u64 v[0:1], v[2:3], 0, s[20:21]
	s_mov_b32 m0, s45
	s_addc_u32 s11, s7, 0
	global_load_lds_dwordx4 v[0:1], off
	s_add_i32 m0, s39, 0x1c000
	v_lshl_add_u64 v[0:1], s[10:11], 0, v[132:133]
	global_load_lds_dwordx4 v[0:1], off
	v_lshl_add_u64 v[0:1], s[10:11], 0, v[128:129]
	s_add_i32 m0, s39, 0x1e000
	s_sext_i32_i16 s1, s2
	global_load_lds_dwordx4 v[0:1], off
	s_waitcnt vmcnt(8)
	s_barrier
	v_and_b32_e32 v0, 15, v150
	v_lshlrev_b32_e32 v1, 1, v11
	v_lshlrev_b32_e32 v2, 2, v150
	v_lshlrev_b32_e32 v3, 6, v150
	s_movk_i32 s2, 0x3c0
	v_lshl_or_b32 v149, s8, 6, v0
	v_lshl_or_b32 v0, v0, 6, v1
	v_and_b32_e32 v2, 32, v2
	v_and_or_b32 v1, v3, s2, v1
	v_bitop3_b32 v151, s23, v1, v2 bitop3:0xf6
	v_lshlrev_b32_e32 v1, 8, v150
	v_bitop3_b32 v0, v0, s22, v2 bitop3:0xde
	v_and_b32_e32 v1, 0x38000, v1
	v_lshlrev_b32_e32 v2, 11, v12
	v_or3_b32 v1, v9, v1, v2
	v_add_u32_e32 v136, v1, v10
	v_lshlrev_b32_e32 v1, 4, v8
	s_waitcnt vmcnt(6)
	s_cmpk_lt_u32 s3, 0x100
	v_and_b32_e32 v1, 0x78000, v1
	s_cselect_b64 s[22:23], -1, 0
	v_or3_b32 v1, v9, v1, v2
	s_add_i32 s47, 0, 0x10000
	s_add_i32 s50, 0, 0x14000
	s_ashr_i32 s46, s89, 31
	v_or_b32_e32 v154, s9, v11
	v_mov_b32_e32 v137, v133
	v_add_u32_e32 v138, v1, v10
	v_mov_b32_e32 v139, v133
	v_mov_b64_e32 v[140:141], 0x580
	v_mov_b64_e32 v[142:143], 0x57f
	v_add_u32_e32 v155, s47, v151
	v_add_u32_e32 v156, s50, v151
	v_add_u32_e32 v157, 0, v0
	v_mov_b32_e32 v158, 0x358637bd
	s_mov_b32 s51, 0x800000
	s_movk_i32 s52, 0x1600
	s_barrier
	s_branch .LBB0_1663

; #define PG8_STAGE(bufoff, gbase, voff) do { _Pragma("unroll") for (int _i = 0; _i < 2; ++_i) \
;         __builtin_amdgcn_global_load_lds((const unsigned*)((const char*)(gbase) + (voff)[_i]), (PG8_LAS unsigned*)(lds + (bufoff) + ldsw + _i * 8192), 16, 0, 0); } while (0)
; #define PG8_WAIT_V(n) asm volatile("s_waitcnt vmcnt(" #n ")" ::: "memory")
; #define PG8_BAR __builtin_amdgcn_s_barrier()
; template <class Epi, class Sched, bool ALIGN_EPI = false, bool SP2 = false>
; __device__ __forceinline__ void gemm_phase(PG8_LAS unsigned char* lds, const Gemm g, const Sched& S, const Epi& E) {
;     ...
;     if constexpr (SP2) {
;         PG8_STAGE(PG8_SB(0, 0), cB, voffB); PG8_STAGE(PG8_SB(0, 1), cB + hstep, voffB); PG8_STAGE(PG8_SA(0, 0), cA, voffA); PG8_STAGE(PG8_SA(0, 1), cA + hstep, voffA);
;         if (wr == 1) PG8_BAR;
;         PG8_WAIT_V(2); PG8_BAR;
;         PG8_STAGE(PG8_SB(1, 0), cB + kstep, voffB); PG8_STAGE(PG8_SA(1, 0), cA + kstep, voffA); PG8_STAGE(PG8_SB(1, 1), cB + hstep + kstep, voffB);
;         PG8_WAIT_V(6); PG8_BAR;
.LBB0_1737:
	s_lshl_b32 s1, s1, 5
	s_mov_b64 s[14:15], 0x80
	s_and_b32 s1, s1, 0x60
	s_add_i32 m0, s27, 0x18000
	v_lshl_add_u64 v[6:7], v[6:7], 0, s[14:15]
	s_lshl_b32 s5, s0, 13
	s_lshl_b32 s6, s1, 7
	global_load_lds_dwordx4 v[6:7], off
	v_lshl_add_u64 v[4:5], v[4:5], 0, s[14:15]
	s_add_i32 m0, s27, 0x1a000
	s_add_i32 s34, s27, 0x8000
	s_add_i32 s35, s27, 0xa000
	global_load_lds_dwordx4 v[4:5], off
	v_lshl_add_u64 v[0:1], v[0:1], 0, s[14:15]
	s_mov_b32 m0, s34
	s_add_u32 s2, s22, 0xb0080
	global_load_lds_dwordx4 v[0:1], off
	v_lshl_add_u64 v[0:1], v[2:3], 0, s[14:15]
	s_mov_b32 m0, s35
	s_addc_u32 s3, s23, 0
	global_load_lds_dwordx4 v[0:1], off
	s_add_i32 m0, s27, 0x1c000
	v_lshl_add_u64 v[0:1], s[2:3], 0, v[128:129]
	global_load_lds_dwordx4 v[0:1], off
	v_lshl_add_u64 v[0:1], s[2:3], 0, v[130:131]
	s_add_i32 m0, s27, 0x1e000
	v_lshlrev_b32_e32 v3, 2, v150
	global_load_lds_dwordx4 v[0:1], off
	s_waitcnt vmcnt(8)
	s_barrier
	v_bfe_u32 v1, v150, 4, 2
	v_and_b32_e32 v0, 15, v150
	v_lshlrev_b32_e32 v2, 4, v1
	v_lshl_or_b32 v149, s0, 6, v0
	v_lshl_or_b32 v0, v0, 6, v2
	v_and_b32_e32 v3, 32, v3
	v_lshlrev_b32_e32 v4, 6, v150
	s_movk_i32 s0, 0x3c0
	v_bitop3_b32 v0, v0, s5, v3 bitop3:0xde
	v_and_or_b32 v2, v4, s0, v2
	s_waitcnt vmcnt(6)
	s_cmpk_lt_u32 s4, 0x100
	v_bitop3_b32 v192, s6, v2, v3 bitop3:0xf6
	s_cselect_b64 s[16:17], -1, 0
	s_add_i32 s38, 0, 0x10000
	s_add_i32 s39, 0, 0x14000
	v_add_u32_e32 v196, 0, v0
	v_mbcnt_lo_u32_b32 v0, -1, 0
	v_cmp_eq_u32_e64 s[2:3], 0, v1
	v_cmp_eq_u32_e64 s[4:5], 0, v148
	s_ashr_i32 s36, s89, 31
	s_ashr_i32 s37, s33, 31
	v_lshl_or_b32 v193, v1, 2, s1
	v_add3_u32 v132, v10, v8, v9
	v_mov_b32_e32 v133, v129
	v_add3_u32 v134, v11, v8, v9
	v_mov_b32_e32 v135, v129
	v_mov_b64_e32 v[136:137], 0x100
	v_mov_b64_e32 v[138:139], 0xff
	v_add_u32_e32 v194, s38, v192
	v_add_u32_e32 v195, s39, v192
	v_mbcnt_hi_u32_b32 v197, -1, v0
	v_mov_b32_e32 v198, 0x358637bd
	s_mov_b32 s40, 0x800000
	s_barrier
	s_branch .LBB0_1740

; DI unsigned pk2(float lo, float hi) { f32x2_t v = {lo, hi}; bf16x2_t b = __builtin_convertvector(v, bf16x2_t); return __builtin_bit_cast(unsigned, b); }
;     DI void operator()(AccRef acc, const Unit& u, int wr, int wc, int fr, int fq) const {
;         const int row0 = rowoff + u.pm * BM + wr * 64 + fr, col0 = u.pn * BM + wc * 32 + 4 * fq;
; #pragma unroll
;         for (int ai = 0; ai < 2; ++ai)
; #pragma unroll
;             for (int m = 0; m < 4; ++m) {
;                 const int row = row0 + ai * HALF + m * 16; float ss = 0.f;
; #pragma unroll
;                 for (int bj = 0; bj < 2; ++bj)
; #pragma unroll
;                     for (int n = 0; n < 2; ++n) {
;                         const int col = col0 + bj * HALF + n * 16;
;                         const f32x4 x = base4(row, col) + acc[ai][bj][m][n];
;                         ss += (x[0] * x[0] + x[1] * x[1]) + (x[2] * x[2] + x[3] * x[3]);
;                         if (FIRST && !dry) { u32x2 w; w.x = pk2(x[0], x[1]); w.y = pk2(x[2], x[3]); *(u32x2*)(XB + (size_t)row * DM + col) = w; }
;                     }
;                 ss += __shfl_xor(ss, 16); ss += __shfl_xor(ss, 32);
;                 if (fq == 0 && !dry) unsafeAtomicAdd(SS + row, ss);
;             }
.LBB0_1754:
	s_lshl_b32 s20, s43, 8
	s_add_u32 s20, s20, 0x4000
	s_lshl_b32 s21, s20, 11
	s_lshl_b32 s98, s44, 9
	s_add_u32 s21, s21, s98
	v_lshlrev_b32_e32 v228, 11, v149
	v_lshl_add_u32 v228, v193, 1, v228
	v_add_u32_e32 v228, s21, v228
	s_lshl_b32 s21, s20, 2
	v_lshlrev_b32_e32 v229, 2, v149
	v_add_u32_e32 v229, s21, v229
	s_lshl_b32 s21, s20, 12
	s_lshl_b32 s98, s44, 10
	s_add_u32 s21, s21, s98
	v_lshlrev_b32_e32 v230, 12, v149
	v_lshl_add_u32 v230, v193, 2, v230
	v_add_u32_e32 v230, s21, v230
	v_lshlrev_b32_e32 v231, 2, v193
	v_add_u32_e32 v231, s98, v231
	v_xor_b32_e32 v232, 16, v197
	v_lshlrev_b32_e32 v232, 2, v232
	v_xor_b32_e32 v233, 32, v197
	v_lshlrev_b32_e32 v233, 2, v233
	global_load_dwordx2 v[152:153], v228, s[92:93]
	global_load_dwordx2 v[154:155], v228, s[92:93] offset:32
	global_load_dwordx2 v[156:157], v228, s[92:93] offset:256
	global_load_dwordx2 v[158:159], v228, s[92:93] offset:288
	v_add_u32_e32 v228, 0x8000, v228
	global_load_dwordx2 v[160:161], v228, s[92:93]
	global_load_dwordx2 v[162:163], v228, s[92:93] offset:32
	global_load_dwordx2 v[164:165], v228, s[92:93] offset:256
	global_load_dwordx2 v[166:167], v228, s[92:93] offset:288
	v_add_u32_e32 v228, 0x8000, v228
	global_load_dwordx2 v[168:169], v228, s[92:93]
	global_load_dwordx2 v[170:171], v228, s[92:93] offset:32
	global_load_dwordx2 v[172:173], v228, s[92:93] offset:256
	global_load_dwordx2 v[174:175], v228, s[92:93] offset:288
	v_add_u32_e32 v228, 0x8000, v228
	global_load_dwordx2 v[176:177], v228, s[92:93]
	global_load_dwordx2 v[178:179], v228, s[92:93] offset:32
	global_load_dwordx2 v[180:181], v228, s[92:93] offset:256
	global_load_dwordx2 v[182:183], v228, s[92:93] offset:288
	v_add_u32_e32 v228, 0x28000, v228
	global_load_dwordx2 v[184:185], v228, s[92:93]
	global_load_dwordx2 v[186:187], v228, s[92:93] offset:32
	global_load_dwordx2 v[200:201], v228, s[92:93] offset:256
	global_load_dwordx2 v[202:203], v228, s[92:93] offset:288
	v_add_u32_e32 v228, 0x8000, v228
	global_load_dwordx2 v[204:205], v228, s[92:93]
	global_load_dwordx2 v[206:207], v228, s[92:93] offset:32
	global_load_dwordx2 v[208:209], v228, s[92:93] offset:256
	global_load_dwordx2 v[210:211], v228, s[92:93] offset:288
	v_add_u32_e32 v228, 0x8000, v228
	global_load_dwordx2 v[212:213], v228, s[92:93]
	global_load_dwordx2 v[214:215], v228, s[92:93] offset:32
	global_load_dwordx2 v[216:217], v228, s[92:93] offset:256
	global_load_dwordx2 v[218:219], v228, s[92:93] offset:288
	v_add_u32_e32 v228, 0x8000, v228
	global_load_dwordx2 v[220:221], v228, s[92:93]
	global_load_dwordx2 v[222:223], v228, s[92:93] offset:32
	global_load_dwordx2 v[224:225], v228, s[92:93] offset:256
	global_load_dwordx2 v[226:227], v228, s[92:93] offset:288
	s_waitcnt vmcnt(28)
	v_lshlrev_b32_e32 v140, 16, v152
	v_and_b32_e32 v141, 0xffff0000, v152
	v_lshlrev_b32_e32 v142, 16, v153
	v_and_b32_e32 v143, 0xffff0000, v153
	v_pk_add_f32 v[126:127], v[126:127], v[142:143]
	v_pk_add_f32 v[124:125], v[124:125], v[140:141]
	v_mul_f32_e32 v144, v125, v125
	v_mul_f32_e32 v145, v127, v127
	v_fmac_f32_e32 v144, v124, v124
	v_fmac_f32_e32 v145, v126, v126
	v_add_f32_e32 v146, v144, v145
	v_lshlrev_b32_e32 v140, 16, v154
	v_and_b32_e32 v141, 0xffff0000, v154
	v_lshlrev_b32_e32 v142, 16, v155
	v_and_b32_e32 v143, 0xffff0000, v155
	v_pk_add_f32 v[122:123], v[122:123], v[142:143]
	v_pk_add_f32 v[120:121], v[120:121], v[140:141]
	v_mul_f32_e32 v144, v121, v121
	v_mul_f32_e32 v145, v123, v123
	v_fmac_f32_e32 v144, v120, v120
	v_fmac_f32_e32 v145, v122, v122
	v_add_f32_e32 v144, v144, v145
	v_add_f32_e32 v146, v146, v144
	v_lshlrev_b32_e32 v140, 16, v156
	v_and_b32_e32 v141, 0xffff0000, v156
	v_lshlrev_b32_e32 v142, 16, v157
	v_and_b32_e32 v143, 0xffff0000, v157
	v_pk_add_f32 v[118:119], v[118:119], v[142:143]
	v_pk_add_f32 v[116:117], v[116:117], v[140:141]
	v_mul_f32_e32 v144, v117, v117
	v_mul_f32_e32 v145, v119, v119
	v_fmac_f32_e32 v144, v116, v116
	v_fmac_f32_e32 v145, v118, v118
	v_add_f32_e32 v144, v144, v145
	v_add_f32_e32 v146, v146, v144
	v_lshlrev_b32_e32 v140, 16, v158
	v_and_b32_e32 v141, 0xffff0000, v158
	v_lshlrev_b32_e32 v142, 16, v159
	v_and_b32_e32 v143, 0xffff0000, v159
	v_pk_add_f32 v[114:115], v[114:115], v[142:143]
	v_pk_add_f32 v[112:113], v[112:113], v[140:141]
	v_mul_f32_e32 v144, v113, v113
	v_mul_f32_e32 v145, v115, v115
	v_fmac_f32_e32 v144, v112, v112
	v_fmac_f32_e32 v145, v114, v114
	v_add_f32_e32 v144, v144, v145
	v_add_f32_e32 v146, v146, v144
	ds_bpermute_b32 v147, v232, v146
	s_waitcnt lgkmcnt(0)
	v_add_f32_e32 v146, v146, v147
	ds_bpermute_b32 v147, v233, v146
	s_waitcnt lgkmcnt(0)
	v_add_f32_e32 v146, v146, v147
	s_and_saveexec_b64 s[20:21], s[2:3]
	global_atomic_add_f32 v229, v146, s[12:13]
	s_or_b64 exec, exec, s[20:21]
	s_waitcnt vmcnt(25)
; DI unsigned pk2(float lo, float hi) { f32x2_t v = {lo, hi}; bf16x2_t b = __builtin_convertvector(v, bf16x2_t); return __builtin_bit_cast(unsigned, b); }
;     DI void operator()(AccRef acc, const Unit& u, int wr, int wc, int fr, int fq) const {
;     ...
;                 const int row = row0 + ai * HALF + m * 16; float ss = 0.f;
; #pragma unroll
;                 for (int bj = 0; bj < 2; ++bj)
; #pragma unroll
;                     for (int n = 0; n < 2; ++n) {
;                         const int col = col0 + bj * HALF + n * 16;
;                         const f32x4 x = base4(row, col) + acc[ai][bj][m][n];
;                         ss += (x[0] * x[0] + x[1] * x[1]) + (x[2] * x[2] + x[3] * x[3]);
;                         if (FIRST && !dry) { u32x2 w; w.x = pk2(x[0], x[1]); w.y = pk2(x[2], x[3]); *(u32x2*)(XB + (size_t)row * DM + col) = w; }
;                     }
;                 ss += __shfl_xor(ss, 16); ss += __shfl_xor(ss, 32);
;                 if (fq == 0 && !dry) unsafeAtomicAdd(SS + row, ss);
	v_lshlrev_b32_e32 v140, 16, v160
	v_and_b32_e32 v141, 0xffff0000, v160
	v_lshlrev_b32_e32 v142, 16, v161
	v_and_b32_e32 v143, 0xffff0000, v161
	v_pk_add_f32 v[110:111], v[110:111], v[142:143]
	v_pk_add_f32 v[108:109], v[108:109], v[140:141]
	v_mul_f32_e32 v144, v109, v109
	v_mul_f32_e32 v145, v111, v111
	v_fmac_f32_e32 v144, v108, v108
	v_fmac_f32_e32 v145, v110, v110
	v_add_f32_e32 v146, v144, v145
	v_lshlrev_b32_e32 v140, 16, v162
	v_and_b32_e32 v141, 0xffff0000, v162
	v_lshlrev_b32_e32 v142, 16, v163
	v_and_b32_e32 v143, 0xffff0000, v163
	v_pk_add_f32 v[106:107], v[106:107], v[142:143]
	v_pk_add_f32 v[104:105], v[104:105], v[140:141]
	v_mul_f32_e32 v144, v105, v105
	v_mul_f32_e32 v145, v107, v107
	v_fmac_f32_e32 v144, v104, v104
	v_fmac_f32_e32 v145, v106, v106
	v_add_f32_e32 v144, v144, v145
	v_add_f32_e32 v146, v146, v144
	v_lshlrev_b32_e32 v140, 16, v164
	v_and_b32_e32 v141, 0xffff0000, v164
	v_lshlrev_b32_e32 v142, 16, v165
	v_and_b32_e32 v143, 0xffff0000, v165
	v_pk_add_f32 v[102:103], v[102:103], v[142:143]
	v_pk_add_f32 v[100:101], v[100:101], v[140:141]
	v_mul_f32_e32 v144, v101, v101
	v_mul_f32_e32 v145, v103, v103
	v_fmac_f32_e32 v144, v100, v100
	v_fmac_f32_e32 v145, v102, v102
	v_add_f32_e32 v144, v144, v145
	v_add_f32_e32 v146, v146, v144
	v_lshlrev_b32_e32 v140, 16, v166
	v_and_b32_e32 v141, 0xffff0000, v166
	v_lshlrev_b32_e32 v142, 16, v167
	v_and_b32_e32 v143, 0xffff0000, v167
	v_pk_add_f32 v[98:99], v[98:99], v[142:143]
	v_pk_add_f32 v[96:97], v[96:97], v[140:141]
	v_mul_f32_e32 v144, v97, v97
	v_mul_f32_e32 v145, v99, v99
	v_fmac_f32_e32 v144, v96, v96
	v_fmac_f32_e32 v145, v98, v98
	v_add_f32_e32 v144, v144, v145
	v_add_f32_e32 v146, v146, v144
	ds_bpermute_b32 v147, v232, v146
	s_waitcnt lgkmcnt(0)
	v_add_f32_e32 v146, v146, v147
	ds_bpermute_b32 v147, v233, v146
	s_waitcnt lgkmcnt(0)
	v_add_f32_e32 v146, v146, v147
	s_and_saveexec_b64 s[20:21], s[2:3]
	global_atomic_add_f32 v229, v146, s[12:13] offset:64
	s_or_b64 exec, exec, s[20:21]
	s_waitcnt vmcnt(22)
	v_lshlrev_b32_e32 v140, 16, v168
	v_and_b32_e32 v141, 0xffff0000, v168
	v_lshlrev_b32_e32 v142, 16, v169
	v_and_b32_e32 v143, 0xffff0000, v169
	v_pk_add_f32 v[94:95], v[94:95], v[142:143]
	v_pk_add_f32 v[92:93], v[92:93], v[140:141]
	v_mul_f32_e32 v144, v93, v93
	v_mul_f32_e32 v145, v95, v95
	v_fmac_f32_e32 v144, v92, v92
	v_fmac_f32_e32 v145, v94, v94
	v_add_f32_e32 v146, v144, v145
	v_lshlrev_b32_e32 v140, 16, v170
	v_and_b32_e32 v141, 0xffff0000, v170
	v_lshlrev_b32_e32 v142, 16, v171
	v_and_b32_e32 v143, 0xffff0000, v171
	v_pk_add_f32 v[90:91], v[90:91], v[142:143]
	v_pk_add_f32 v[88:89], v[88:89], v[140:141]
	v_mul_f32_e32 v144, v89, v89
	v_mul_f32_e32 v145, v91, v91
	v_fmac_f32_e32 v144, v88, v88
	v_fmac_f32_e32 v145, v90, v90
	v_add_f32_e32 v144, v144, v145
	v_add_f32_e32 v146, v146, v144
	v_lshlrev_b32_e32 v140, 16, v172
	v_and_b32_e32 v141, 0xffff0000, v172
	v_lshlrev_b32_e32 v142, 16, v173
	v_and_b32_e32 v143, 0xffff0000, v173
	v_pk_add_f32 v[86:87], v[86:87], v[142:143]
	v_pk_add_f32 v[84:85], v[84:85], v[140:141]
	v_mul_f32_e32 v144, v85, v85
	v_mul_f32_e32 v145, v87, v87
	v_fmac_f32_e32 v144, v84, v84
	v_fmac_f32_e32 v145, v86, v86
	v_add_f32_e32 v144, v144, v145
	v_add_f32_e32 v146, v146, v144
	v_lshlrev_b32_e32 v140, 16, v174
	v_and_b32_e32 v141, 0xffff0000, v174
	v_lshlrev_b32_e32 v142, 16, v175
	v_and_b32_e32 v143, 0xffff0000, v175
	v_pk_add_f32 v[82:83], v[82:83], v[142:143]
	v_pk_add_f32 v[80:81], v[80:81], v[140:141]
	v_mul_f32_e32 v144, v81, v81
	v_mul_f32_e32 v145, v83, v83
	v_fmac_f32_e32 v144, v80, v80
	v_fmac_f32_e32 v145, v82, v82
	v_add_f32_e32 v144, v144, v145
	v_add_f32_e32 v146, v146, v144
	ds_bpermute_b32 v147, v232, v146
	s_waitcnt lgkmcnt(0)
	v_add_f32_e32 v146, v146, v147
	ds_bpermute_b32 v147, v233, v146
	s_waitcnt lgkmcnt(0)
	v_add_f32_e32 v146, v146, v147
	s_and_saveexec_b64 s[20:21], s[2:3]
	global_atomic_add_f32 v229, v146, s[12:13] offset:128
	s_or_b64 exec, exec, s[20:21]
	s_waitcnt vmcnt(19)
	v_lshlrev_b32_e32 v140, 16, v176
	v_and_b32_e32 v141, 0xffff0000, v176
	v_lshlrev_b32_e32 v142, 16, v177
	v_and_b32_e32 v143, 0xffff0000, v177
	v_pk_add_f32 v[78:79], v[78:79], v[142:143]
	v_pk_add_f32 v[76:77], v[76:77], v[140:141]
	v_mul_f32_e32 v144, v77, v77
	v_mul_f32_e32 v145, v79, v79
	v_fmac_f32_e32 v144, v76, v76
	v_fmac_f32_e32 v145, v78, v78
	v_add_f32_e32 v146, v144, v145
	v_lshlrev_b32_e32 v140, 16, v178
	v_and_b32_e32 v141, 0xffff0000, v178
	v_lshlrev_b32_e32 v142, 16, v179
	v_and_b32_e32 v143, 0xffff0000, v179
	v_pk_add_f32 v[74:75], v[74:75], v[142:143]
	v_pk_add_f32 v[72:73], v[72:73], v[140:141]
	v_mul_f32_e32 v144, v73, v73
	v_mul_f32_e32 v145, v75, v75
	v_fmac_f32_e32 v144, v72, v72
	v_fmac_f32_e32 v145, v74, v74
	v_add_f32_e32 v144, v144, v145
	v_add_f32_e32 v146, v146, v144
	v_lshlrev_b32_e32 v140, 16, v180
	v_and_b32_e32 v141, 0xffff0000, v180
	v_lshlrev_b32_e32 v142, 16, v181
	v_and_b32_e32 v143, 0xffff0000, v181
	v_pk_add_f32 v[70:71], v[70:71], v[142:143]
	v_pk_add_f32 v[68:69], v[68:69], v[140:141]
	v_mul_f32_e32 v144, v69, v69
	v_mul_f32_e32 v145, v71, v71
	v_fmac_f32_e32 v144, v68, v68
	v_fmac_f32_e32 v145, v70, v70
	v_add_f32_e32 v144, v144, v145
	v_add_f32_e32 v146, v146, v144
	v_lshlrev_b32_e32 v140, 16, v182
	v_and_b32_e32 v141, 0xffff0000, v182
	v_lshlrev_b32_e32 v142, 16, v183
	v_and_b32_e32 v143, 0xffff0000, v183
	v_pk_add_f32 v[66:67], v[66:67], v[142:143]
	v_pk_add_f32 v[64:65], v[64:65], v[140:141]
	v_mul_f32_e32 v144, v65, v65
	v_mul_f32_e32 v145, v67, v67
	v_fmac_f32_e32 v144, v64, v64
	v_fmac_f32_e32 v145, v66, v66
	v_add_f32_e32 v144, v144, v145
	v_add_f32_e32 v146, v146, v144
	ds_bpermute_b32 v147, v232, v146
	s_waitcnt lgkmcnt(0)
; DI unsigned pk2(float lo, float hi) { f32x2_t v = {lo, hi}; bf16x2_t b = __builtin_convertvector(v, bf16x2_t); return __builtin_bit_cast(unsigned, b); }
;     DI void operator()(AccRef acc, const Unit& u, int wr, int wc, int fr, int fq) const {
;     ...
;                 const int row = row0 + ai * HALF + m * 16; float ss = 0.f;
; #pragma unroll
;                 for (int bj = 0; bj < 2; ++bj)
; #pragma unroll
;                     for (int n = 0; n < 2; ++n) {
;                         const int col = col0 + bj * HALF + n * 16;
;                         const f32x4 x = base4(row, col) + acc[ai][bj][m][n];
;                         ss += (x[0] * x[0] + x[1] * x[1]) + (x[2] * x[2] + x[3] * x[3]);
;                         if (FIRST && !dry) { u32x2 w; w.x = pk2(x[0], x[1]); w.y = pk2(x[2], x[3]); *(u32x2*)(XB + (size_t)row * DM + col) = w; }
;                     }
;                 ss += __shfl_xor(ss, 16); ss += __shfl_xor(ss, 32);
;                 if (fq == 0 && !dry) unsafeAtomicAdd(SS + row, ss);
	v_add_f32_e32 v146, v146, v147
	ds_bpermute_b32 v147, v233, v146
	s_waitcnt lgkmcnt(0)
	v_add_f32_e32 v146, v146, v147
	s_and_saveexec_b64 s[20:21], s[2:3]
	global_atomic_add_f32 v229, v146, s[12:13] offset:192
	s_or_b64 exec, exec, s[20:21]
	s_waitcnt vmcnt(16)
	v_lshlrev_b32_e32 v140, 16, v184
	v_and_b32_e32 v141, 0xffff0000, v184
	v_lshlrev_b32_e32 v142, 16, v185
	v_and_b32_e32 v143, 0xffff0000, v185
	v_pk_add_f32 v[62:63], v[62:63], v[142:143]
	v_pk_add_f32 v[60:61], v[60:61], v[140:141]
	v_mul_f32_e32 v144, v61, v61
	v_mul_f32_e32 v145, v63, v63
	v_fmac_f32_e32 v144, v60, v60
	v_fmac_f32_e32 v145, v62, v62
	v_add_f32_e32 v146, v144, v145
	v_lshlrev_b32_e32 v140, 16, v186
	v_and_b32_e32 v141, 0xffff0000, v186
	v_lshlrev_b32_e32 v142, 16, v187
	v_and_b32_e32 v143, 0xffff0000, v187
	v_pk_add_f32 v[58:59], v[58:59], v[142:143]
	v_pk_add_f32 v[56:57], v[56:57], v[140:141]
	v_mul_f32_e32 v144, v57, v57
	v_mul_f32_e32 v145, v59, v59
	v_fmac_f32_e32 v144, v56, v56
	v_fmac_f32_e32 v145, v58, v58
	v_add_f32_e32 v144, v144, v145
	v_add_f32_e32 v146, v146, v144
	v_lshlrev_b32_e32 v140, 16, v200
	v_and_b32_e32 v141, 0xffff0000, v200
	v_lshlrev_b32_e32 v142, 16, v201
	v_and_b32_e32 v143, 0xffff0000, v201
	v_pk_add_f32 v[54:55], v[54:55], v[142:143]
	v_pk_add_f32 v[52:53], v[52:53], v[140:141]
	v_mul_f32_e32 v144, v53, v53
	v_mul_f32_e32 v145, v55, v55
	v_fmac_f32_e32 v144, v52, v52
	v_fmac_f32_e32 v145, v54, v54
	v_add_f32_e32 v144, v144, v145
	v_add_f32_e32 v146, v146, v144
	v_lshlrev_b32_e32 v140, 16, v202
	v_and_b32_e32 v141, 0xffff0000, v202
	v_lshlrev_b32_e32 v142, 16, v203
	v_and_b32_e32 v143, 0xffff0000, v203
	v_pk_add_f32 v[50:51], v[50:51], v[142:143]
	v_pk_add_f32 v[48:49], v[48:49], v[140:141]
	v_mul_f32_e32 v144, v49, v49
	v_mul_f32_e32 v145, v51, v51
	v_fmac_f32_e32 v144, v48, v48
	v_fmac_f32_e32 v145, v50, v50
	v_add_f32_e32 v144, v144, v145
	v_add_f32_e32 v146, v146, v144
	ds_bpermute_b32 v147, v232, v146
	s_waitcnt lgkmcnt(0)
	v_add_f32_e32 v146, v146, v147
	ds_bpermute_b32 v147, v233, v146
	s_waitcnt lgkmcnt(0)
	v_add_f32_e32 v146, v146, v147
	s_and_saveexec_b64 s[20:21], s[2:3]
	global_atomic_add_f32 v229, v146, s[12:13] offset:512
	s_or_b64 exec, exec, s[20:21]
	s_waitcnt vmcnt(13)
	v_lshlrev_b32_e32 v140, 16, v204
	v_and_b32_e32 v141, 0xffff0000, v204
	v_lshlrev_b32_e32 v142, 16, v205
	v_and_b32_e32 v143, 0xffff0000, v205
	v_pk_add_f32 v[46:47], v[46:47], v[142:143]
	v_pk_add_f32 v[44:45], v[44:45], v[140:141]
	v_mul_f32_e32 v144, v45, v45
	v_mul_f32_e32 v145, v47, v47
	v_fmac_f32_e32 v144, v44, v44
	v_fmac_f32_e32 v145, v46, v46
	v_add_f32_e32 v146, v144, v145
	v_lshlrev_b32_e32 v140, 16, v206
	v_and_b32_e32 v141, 0xffff0000, v206
	v_lshlrev_b32_e32 v142, 16, v207
	v_and_b32_e32 v143, 0xffff0000, v207
	v_pk_add_f32 v[42:43], v[42:43], v[142:143]
	v_pk_add_f32 v[40:41], v[40:41], v[140:141]
	v_mul_f32_e32 v144, v41, v41
	v_mul_f32_e32 v145, v43, v43
	v_fmac_f32_e32 v144, v40, v40
	v_fmac_f32_e32 v145, v42, v42
	v_add_f32_e32 v144, v144, v145
	v_add_f32_e32 v146, v146, v144
	v_lshlrev_b32_e32 v140, 16, v208
	v_and_b32_e32 v141, 0xffff0000, v208
	v_lshlrev_b32_e32 v142, 16, v209
	v_and_b32_e32 v143, 0xffff0000, v209
	v_pk_add_f32 v[38:39], v[38:39], v[142:143]
	v_pk_add_f32 v[36:37], v[36:37], v[140:141]
	v_mul_f32_e32 v144, v37, v37
	v_mul_f32_e32 v145, v39, v39
	v_fmac_f32_e32 v144, v36, v36
	v_fmac_f32_e32 v145, v38, v38
	v_add_f32_e32 v144, v144, v145
	v_add_f32_e32 v146, v146, v144
	v_lshlrev_b32_e32 v140, 16, v210
	v_and_b32_e32 v141, 0xffff0000, v210
	v_lshlrev_b32_e32 v142, 16, v211
	v_and_b32_e32 v143, 0xffff0000, v211
	v_pk_add_f32 v[34:35], v[34:35], v[142:143]
	v_pk_add_f32 v[32:33], v[32:33], v[140:141]
	v_mul_f32_e32 v144, v33, v33
	v_mul_f32_e32 v145, v35, v35
	v_fmac_f32_e32 v144, v32, v32
	v_fmac_f32_e32 v145, v34, v34
	v_add_f32_e32 v144, v144, v145
	v_add_f32_e32 v146, v146, v144
	ds_bpermute_b32 v147, v232, v146
	s_waitcnt lgkmcnt(0)
	v_add_f32_e32 v146, v146, v147
	ds_bpermute_b32 v147, v233, v146
	s_waitcnt lgkmcnt(0)
	v_add_f32_e32 v146, v146, v147
	s_and_saveexec_b64 s[20:21], s[2:3]
	global_atomic_add_f32 v229, v146, s[12:13] offset:576
	s_or_b64 exec, exec, s[20:21]
	s_waitcnt vmcnt(10)
; DI unsigned pk2(float lo, float hi) { f32x2_t v = {lo, hi}; bf16x2_t b = __builtin_convertvector(v, bf16x2_t); return __builtin_bit_cast(unsigned, b); }
;     DI void operator()(AccRef acc, const Unit& u, int wr, int wc, int fr, int fq) const {
;     ...
;                 const int row = row0 + ai * HALF + m * 16; float ss = 0.f;
; #pragma unroll
;                 for (int bj = 0; bj < 2; ++bj)
; #pragma unroll
;                     for (int n = 0; n < 2; ++n) {
;                         const int col = col0 + bj * HALF + n * 16;
;                         const f32x4 x = base4(row, col) + acc[ai][bj][m][n];
;                         ss += (x[0] * x[0] + x[1] * x[1]) + (x[2] * x[2] + x[3] * x[3]);
;                         if (FIRST && !dry) { u32x2 w; w.x = pk2(x[0], x[1]); w.y = pk2(x[2], x[3]); *(u32x2*)(XB + (size_t)row * DM + col) = w; }
;                     }
;                 ss += __shfl_xor(ss, 16); ss += __shfl_xor(ss, 32);
;                 if (fq == 0 && !dry) unsafeAtomicAdd(SS + row, ss);
;             }
;         if (FUSE) {
;             unsigned* pc = cnt + 16 * ((rowoff >> 8) + u.pm);
;             asm volatile("s_waitcnt vmcnt(0)" ::: "memory");
;             if ((threadIdx.x & 63) == 0) __hip_atomic_fetch_add(pc, 1u, __ATOMIC_RELAXED, __HIP_MEMORY_SCOPE_AGENT);
	v_lshlrev_b32_e32 v140, 16, v212
	v_and_b32_e32 v141, 0xffff0000, v212
	v_lshlrev_b32_e32 v142, 16, v213
	v_and_b32_e32 v143, 0xffff0000, v213
	v_pk_add_f32 v[30:31], v[30:31], v[142:143]
	v_pk_add_f32 v[28:29], v[28:29], v[140:141]
	v_mul_f32_e32 v144, v29, v29
	v_mul_f32_e32 v145, v31, v31
	v_fmac_f32_e32 v144, v28, v28
	v_fmac_f32_e32 v145, v30, v30
	v_add_f32_e32 v146, v144, v145
	v_lshlrev_b32_e32 v140, 16, v214
	v_and_b32_e32 v141, 0xffff0000, v214
	v_lshlrev_b32_e32 v142, 16, v215
	v_and_b32_e32 v143, 0xffff0000, v215
	v_pk_add_f32 v[26:27], v[26:27], v[142:143]
	v_pk_add_f32 v[24:25], v[24:25], v[140:141]
	v_mul_f32_e32 v144, v25, v25
	v_mul_f32_e32 v145, v27, v27
	v_fmac_f32_e32 v144, v24, v24
	v_fmac_f32_e32 v145, v26, v26
	v_add_f32_e32 v144, v144, v145
	v_add_f32_e32 v146, v146, v144
	v_lshlrev_b32_e32 v140, 16, v216
	v_and_b32_e32 v141, 0xffff0000, v216
	v_lshlrev_b32_e32 v142, 16, v217
	v_and_b32_e32 v143, 0xffff0000, v217
	v_pk_add_f32 v[22:23], v[22:23], v[142:143]
	v_pk_add_f32 v[20:21], v[20:21], v[140:141]
	v_mul_f32_e32 v144, v21, v21
	v_mul_f32_e32 v145, v23, v23
	v_fmac_f32_e32 v144, v20, v20
	v_fmac_f32_e32 v145, v22, v22
	v_add_f32_e32 v144, v144, v145
	v_add_f32_e32 v146, v146, v144
	v_lshlrev_b32_e32 v140, 16, v218
	v_and_b32_e32 v141, 0xffff0000, v218
	v_lshlrev_b32_e32 v142, 16, v219
	v_and_b32_e32 v143, 0xffff0000, v219
	v_pk_add_f32 v[18:19], v[18:19], v[142:143]
	v_pk_add_f32 v[16:17], v[16:17], v[140:141]
	v_mul_f32_e32 v144, v17, v17
	v_mul_f32_e32 v145, v19, v19
	v_fmac_f32_e32 v144, v16, v16
	v_fmac_f32_e32 v145, v18, v18
	v_add_f32_e32 v144, v144, v145
	v_add_f32_e32 v146, v146, v144
	ds_bpermute_b32 v147, v232, v146
	s_waitcnt lgkmcnt(0)
	v_add_f32_e32 v146, v146, v147
	ds_bpermute_b32 v147, v233, v146
	s_waitcnt lgkmcnt(0)
	v_add_f32_e32 v146, v146, v147
	s_and_saveexec_b64 s[20:21], s[2:3]
	global_atomic_add_f32 v229, v146, s[12:13] offset:640
	s_or_b64 exec, exec, s[20:21]
	s_waitcnt vmcnt(7)
	v_lshlrev_b32_e32 v140, 16, v220
	v_and_b32_e32 v141, 0xffff0000, v220
	v_lshlrev_b32_e32 v142, 16, v221
	v_and_b32_e32 v143, 0xffff0000, v221
	v_pk_add_f32 v[14:15], v[14:15], v[142:143]
	v_pk_add_f32 v[12:13], v[12:13], v[140:141]
	v_mul_f32_e32 v144, v13, v13
	v_mul_f32_e32 v145, v15, v15
	v_fmac_f32_e32 v144, v12, v12
	v_fmac_f32_e32 v145, v14, v14
	v_add_f32_e32 v146, v144, v145
	v_lshlrev_b32_e32 v140, 16, v222
	v_and_b32_e32 v141, 0xffff0000, v222
	v_lshlrev_b32_e32 v142, 16, v223
	v_and_b32_e32 v143, 0xffff0000, v223
	v_pk_add_f32 v[10:11], v[10:11], v[142:143]
	v_pk_add_f32 v[8:9], v[8:9], v[140:141]
	v_mul_f32_e32 v144, v9, v9
	v_mul_f32_e32 v145, v11, v11
	v_fmac_f32_e32 v144, v8, v8
	v_fmac_f32_e32 v145, v10, v10
	v_add_f32_e32 v144, v144, v145
	v_add_f32_e32 v146, v146, v144
	v_lshlrev_b32_e32 v140, 16, v224
	v_and_b32_e32 v141, 0xffff0000, v224
	v_lshlrev_b32_e32 v142, 16, v225
	v_and_b32_e32 v143, 0xffff0000, v225
	v_pk_add_f32 v[6:7], v[6:7], v[142:143]
	v_pk_add_f32 v[4:5], v[4:5], v[140:141]
	v_mul_f32_e32 v144, v5, v5
	v_mul_f32_e32 v145, v7, v7
	v_fmac_f32_e32 v144, v4, v4
	v_fmac_f32_e32 v145, v6, v6
	v_add_f32_e32 v144, v144, v145
	v_add_f32_e32 v146, v146, v144
	v_lshlrev_b32_e32 v140, 16, v226
	v_and_b32_e32 v141, 0xffff0000, v226
	v_lshlrev_b32_e32 v142, 16, v227
	v_and_b32_e32 v143, 0xffff0000, v227
	v_pk_add_f32 v[2:3], v[2:3], v[142:143]
	v_pk_add_f32 v[0:1], v[0:1], v[140:141]
	v_mul_f32_e32 v144, v1, v1
	v_mul_f32_e32 v145, v3, v3
	v_fmac_f32_e32 v144, v0, v0
	v_fmac_f32_e32 v145, v2, v2
	v_add_f32_e32 v144, v144, v145
	v_add_f32_e32 v146, v146, v144
	ds_bpermute_b32 v147, v232, v146
	s_waitcnt lgkmcnt(0)
	v_add_f32_e32 v146, v146, v147
	ds_bpermute_b32 v147, v233, v146
	s_waitcnt lgkmcnt(0)
	v_add_f32_e32 v146, v146, v147
	s_and_saveexec_b64 s[20:21], s[2:3]
	global_atomic_add_f32 v229, v146, s[12:13] offset:704
	s_or_b64 exec, exec, s[20:21]
	s_lshl_b32 s20, s43, 4
	s_addk_i32 s20, 0x400
	s_ashr_i32 s21, s20, 31
	s_lshl_b64 s[20:21], s[20:21], 2
	s_waitcnt vmcnt(0)
	s_add_u32 s20, s60, s20
	s_addc_u32 s21, s61, s21
	s_and_saveexec_b64 s[22:23], s[4:5]
	s_cbranch_execz .LBB0_1773
	s_mov_b64 s[24:25], exec
	v_mbcnt_lo_u32_b32 v242, s24, 0
	v_mbcnt_hi_u32_b32 v242, s25, v242
	v_cmp_eq_u32_e32 vcc, 0, v242
	s_and_b64 s[44:45], exec, vcc
	s_mov_b64 exec, s[44:45]
	s_cbranch_execz .LBB0_1773
	s_bcnt1_i32_b64 s24, s[24:25]
	v_mov_b32_e32 v242, s24
	global_atomic_add v129, v242, s[20:21]

;     DI void operator()(AccRef acc, const Unit& u, int wr, int wc, int fr, int fq) const {
;     ...
;             unsigned spins = 0;
;             for (;;) { const unsigned v = __hip_atomic_load(pc, __ATOMIC_RELAXED, __HIP_MEMORY_SCOPE_AGENT);
;                 if ((unsigned)__builtin_amdgcn_readfirstlane(v) >= 32u || ++spins > (1u << 22)) break; __builtin_amdgcn_s_sleep(2); }
;             __builtin_amdgcn_fence(__ATOMIC_ACQUIRE, "agent");
; #pragma unroll
;             for (int ai = 0; ai < 2; ++ai)
; #pragma unroll
;                 for (int m = 0; m < 4; ++m) {
;                     const int row = row0 + ai * HALF + m * 16;
;                     const float rs = rsqrtf(__hip_atomic_load(SS + row, __ATOMIC_RELAXED, __HIP_MEMORY_SCOPE_AGENT) * (1.0f / DM) + EPSN);
; #pragma unroll
;                     for (int bj = 0; bj < 2; ++bj)
; #pragma unroll
;                         for (int n = 0; n < 2; ++n) {
;                             const int col = col0 + bj * HALF + n * 16;
;                             const f32x4 x = base4(row, col) + acc[ai][bj][m][n];
;                             if (!dry) *(f32x4*)(out + (size_t)row * DM + col) = x * rs * *(const f32x4*)(gain + col);
.LBB0_1777:
	buffer_inv sc1
	global_load_dword v234, v229, s[12:13] sc1
	global_load_dword v235, v229, s[12:13] offset:64 sc1
	global_load_dword v236, v229, s[12:13] offset:128 sc1
	global_load_dword v237, v229, s[12:13] offset:192 sc1
	global_load_dword v238, v229, s[12:13] offset:512 sc1
	global_load_dword v239, v229, s[12:13] offset:576 sc1
	global_load_dword v240, v229, s[12:13] offset:640 sc1
	global_load_dword v241, v229, s[12:13] offset:704 sc1
	global_load_dwordx4 v[152:155], v231, s[62:63]
	global_load_dwordx4 v[156:159], v231, s[62:63] offset:64
	global_load_dwordx4 v[160:163], v231, s[62:63] offset:512
	global_load_dwordx4 v[164:167], v231, s[62:63] offset:576
	s_waitcnt vmcnt(0)
	v_fmamk_f32 v244, v234, 0x3a800000, v198
	v_mul_f32_e32 v140, 0x4b800000, v244
	v_cmp_gt_f32_e32 vcc, s40, v244
	s_nop 1
	v_cndmask_b32_e32 v244, v244, v140, vcc
	v_rsq_f32_e32 v244, v244
	s_nop 0
	v_mul_f32_e32 v140, 0x45800000, v244
	v_cndmask_b32_e32 v244, v244, v140, vcc
	v_pk_mul_f32 v[124:125], v[124:125], v[244:245] op_sel_hi:[1,0]
	v_pk_mul_f32 v[126:127], v[126:127], v[244:245] op_sel_hi:[1,0]
	v_pk_mul_f32 v[124:125], v[152:153], v[124:125]
	v_pk_mul_f32 v[126:127], v[154:155], v[126:127]
	global_store_dwordx4 v230, v[124:127], s[80:81]
	v_pk_mul_f32 v[120:121], v[120:121], v[244:245] op_sel_hi:[1,0]
	v_pk_mul_f32 v[122:123], v[122:123], v[244:245] op_sel_hi:[1,0]
	v_pk_mul_f32 v[120:121], v[156:157], v[120:121]
	v_pk_mul_f32 v[122:123], v[158:159], v[122:123]
	global_store_dwordx4 v230, v[120:123], s[80:81] offset:64
	v_pk_mul_f32 v[116:117], v[116:117], v[244:245] op_sel_hi:[1,0]
	v_pk_mul_f32 v[118:119], v[118:119], v[244:245] op_sel_hi:[1,0]
	v_pk_mul_f32 v[116:117], v[160:161], v[116:117]
	v_pk_mul_f32 v[118:119], v[162:163], v[118:119]
	global_store_dwordx4 v230, v[116:119], s[80:81] offset:512
	v_pk_mul_f32 v[112:113], v[112:113], v[244:245] op_sel_hi:[1,0]
	v_pk_mul_f32 v[114:115], v[114:115], v[244:245] op_sel_hi:[1,0]
	v_pk_mul_f32 v[112:113], v[164:165], v[112:113]
	v_pk_mul_f32 v[114:115], v[166:167], v[114:115]
	global_store_dwordx4 v230, v[112:115], s[80:81] offset:576
	v_add_u32_e32 v230, 0x10000, v230
	s_waitcnt vmcnt(14)
	v_fmamk_f32 v244, v235, 0x3a800000, v198
	v_mul_f32_e32 v140, 0x4b800000, v244
	v_cmp_gt_f32_e32 vcc, s40, v244
	s_nop 1
	v_cndmask_b32_e32 v244, v244, v140, vcc
	v_rsq_f32_e32 v244, v244
	s_nop 0
	v_mul_f32_e32 v140, 0x45800000, v244
	v_cndmask_b32_e32 v244, v244, v140, vcc
	v_pk_mul_f32 v[108:109], v[108:109], v[244:245] op_sel_hi:[1,0]
	v_pk_mul_f32 v[110:111], v[110:111], v[244:245] op_sel_hi:[1,0]
	v_pk_mul_f32 v[108:109], v[152:153], v[108:109]
	v_pk_mul_f32 v[110:111], v[154:155], v[110:111]
	global_store_dwordx4 v230, v[108:111], s[80:81]
	v_pk_mul_f32 v[104:105], v[104:105], v[244:245] op_sel_hi:[1,0]
	v_pk_mul_f32 v[106:107], v[106:107], v[244:245] op_sel_hi:[1,0]
	v_pk_mul_f32 v[104:105], v[156:157], v[104:105]
	v_pk_mul_f32 v[106:107], v[158:159], v[106:107]
	global_store_dwordx4 v230, v[104:107], s[80:81] offset:64
	v_pk_mul_f32 v[100:101], v[100:101], v[244:245] op_sel_hi:[1,0]
	v_pk_mul_f32 v[102:103], v[102:103], v[244:245] op_sel_hi:[1,0]
	v_pk_mul_f32 v[100:101], v[160:161], v[100:101]
	v_pk_mul_f32 v[102:103], v[162:163], v[102:103]
	global_store_dwordx4 v230, v[100:103], s[80:81] offset:512
	v_pk_mul_f32 v[96:97], v[96:97], v[244:245] op_sel_hi:[1,0]
	v_pk_mul_f32 v[98:99], v[98:99], v[244:245] op_sel_hi:[1,0]
	v_pk_mul_f32 v[96:97], v[164:165], v[96:97]
	v_pk_mul_f32 v[98:99], v[166:167], v[98:99]
	global_store_dwordx4 v230, v[96:99], s[80:81] offset:576
	v_add_u32_e32 v230, 0x10000, v230
	s_waitcnt vmcnt(17)
	v_fmamk_f32 v244, v236, 0x3a800000, v198
	v_mul_f32_e32 v140, 0x4b800000, v244
	v_cmp_gt_f32_e32 vcc, s40, v244
	s_nop 1
	v_cndmask_b32_e32 v244, v244, v140, vcc
	v_rsq_f32_e32 v244, v244
	s_nop 0
	v_mul_f32_e32 v140, 0x45800000, v244
	v_cndmask_b32_e32 v244, v244, v140, vcc
	v_pk_mul_f32 v[92:93], v[92:93], v[244:245] op_sel_hi:[1,0]
	v_pk_mul_f32 v[94:95], v[94:95], v[244:245] op_sel_hi:[1,0]
	v_pk_mul_f32 v[92:93], v[152:153], v[92:93]
	v_pk_mul_f32 v[94:95], v[154:155], v[94:95]
	global_store_dwordx4 v230, v[92:95], s[80:81]
	v_pk_mul_f32 v[88:89], v[88:89], v[244:245] op_sel_hi:[1,0]
	v_pk_mul_f32 v[90:91], v[90:91], v[244:245] op_sel_hi:[1,0]
	v_pk_mul_f32 v[88:89], v[156:157], v[88:89]
	v_pk_mul_f32 v[90:91], v[158:159], v[90:91]
	global_store_dwordx4 v230, v[88:91], s[80:81] offset:64
	v_pk_mul_f32 v[84:85], v[84:85], v[244:245] op_sel_hi:[1,0]
	v_pk_mul_f32 v[86:87], v[86:87], v[244:245] op_sel_hi:[1,0]
	v_pk_mul_f32 v[84:85], v[160:161], v[84:85]
	v_pk_mul_f32 v[86:87], v[162:163], v[86:87]
	global_store_dwordx4 v230, v[84:87], s[80:81] offset:512
	v_pk_mul_f32 v[80:81], v[80:81], v[244:245] op_sel_hi:[1,0]
	v_pk_mul_f32 v[82:83], v[82:83], v[244:245] op_sel_hi:[1,0]
	v_pk_mul_f32 v[80:81], v[164:165], v[80:81]
	v_pk_mul_f32 v[82:83], v[166:167], v[82:83]
	global_store_dwordx4 v230, v[80:83], s[80:81] offset:576
	v_add_u32_e32 v230, 0x10000, v230
	s_waitcnt vmcnt(20)
;     DI void operator()(AccRef acc, const Unit& u, int wr, int wc, int fr, int fq) const {
;     ...
; #pragma unroll
;             for (int ai = 0; ai < 2; ++ai)
; #pragma unroll
;                 for (int m = 0; m < 4; ++m) {
;                     const int row = row0 + ai * HALF + m * 16;
;                     const float rs = rsqrtf(__hip_atomic_load(SS + row, __ATOMIC_RELAXED, __HIP_MEMORY_SCOPE_AGENT) * (1.0f / DM) + EPSN);
; #pragma unroll
;                     for (int bj = 0; bj < 2; ++bj)
; #pragma unroll
;                         for (int n = 0; n < 2; ++n) {
;                             const int col = col0 + bj * HALF + n * 16;
;                             const f32x4 x = base4(row, col) + acc[ai][bj][m][n];
;                             if (!dry) *(f32x4*)(out + (size_t)row * DM + col) = x * rs * *(const f32x4*)(gain + col);
	v_fmamk_f32 v244, v237, 0x3a800000, v198
	v_mul_f32_e32 v140, 0x4b800000, v244
	v_cmp_gt_f32_e32 vcc, s40, v244
	s_nop 1
	v_cndmask_b32_e32 v244, v244, v140, vcc
	v_rsq_f32_e32 v244, v244
	s_nop 0
	v_mul_f32_e32 v140, 0x45800000, v244
	v_cndmask_b32_e32 v244, v244, v140, vcc
	v_pk_mul_f32 v[76:77], v[76:77], v[244:245] op_sel_hi:[1,0]
	v_pk_mul_f32 v[78:79], v[78:79], v[244:245] op_sel_hi:[1,0]
	v_pk_mul_f32 v[76:77], v[152:153], v[76:77]
	v_pk_mul_f32 v[78:79], v[154:155], v[78:79]
	global_store_dwordx4 v230, v[76:79], s[80:81]
	v_pk_mul_f32 v[72:73], v[72:73], v[244:245] op_sel_hi:[1,0]
	v_pk_mul_f32 v[74:75], v[74:75], v[244:245] op_sel_hi:[1,0]
	v_pk_mul_f32 v[72:73], v[156:157], v[72:73]
	v_pk_mul_f32 v[74:75], v[158:159], v[74:75]
	global_store_dwordx4 v230, v[72:75], s[80:81] offset:64
	v_pk_mul_f32 v[68:69], v[68:69], v[244:245] op_sel_hi:[1,0]
	v_pk_mul_f32 v[70:71], v[70:71], v[244:245] op_sel_hi:[1,0]
	v_pk_mul_f32 v[68:69], v[160:161], v[68:69]
	v_pk_mul_f32 v[70:71], v[162:163], v[70:71]
	global_store_dwordx4 v230, v[68:71], s[80:81] offset:512
	v_pk_mul_f32 v[64:65], v[64:65], v[244:245] op_sel_hi:[1,0]
	v_pk_mul_f32 v[66:67], v[66:67], v[244:245] op_sel_hi:[1,0]
	v_pk_mul_f32 v[64:65], v[164:165], v[64:65]
	v_pk_mul_f32 v[66:67], v[166:167], v[66:67]
	global_store_dwordx4 v230, v[64:67], s[80:81] offset:576
	v_add_u32_e32 v230, 0x50000, v230
	s_waitcnt vmcnt(23)
	v_fmamk_f32 v244, v238, 0x3a800000, v198
	v_mul_f32_e32 v140, 0x4b800000, v244
	v_cmp_gt_f32_e32 vcc, s40, v244
	s_nop 1
	v_cndmask_b32_e32 v244, v244, v140, vcc
	v_rsq_f32_e32 v244, v244
	s_nop 0
	v_mul_f32_e32 v140, 0x45800000, v244
	v_cndmask_b32_e32 v244, v244, v140, vcc
	v_pk_mul_f32 v[60:61], v[60:61], v[244:245] op_sel_hi:[1,0]
	v_pk_mul_f32 v[62:63], v[62:63], v[244:245] op_sel_hi:[1,0]
	v_pk_mul_f32 v[60:61], v[152:153], v[60:61]
	v_pk_mul_f32 v[62:63], v[154:155], v[62:63]
	global_store_dwordx4 v230, v[60:63], s[80:81]
	v_pk_mul_f32 v[56:57], v[56:57], v[244:245] op_sel_hi:[1,0]
	v_pk_mul_f32 v[58:59], v[58:59], v[244:245] op_sel_hi:[1,0]
	v_pk_mul_f32 v[56:57], v[156:157], v[56:57]
	v_pk_mul_f32 v[58:59], v[158:159], v[58:59]
	global_store_dwordx4 v230, v[56:59], s[80:81] offset:64
	v_pk_mul_f32 v[52:53], v[52:53], v[244:245] op_sel_hi:[1,0]
	v_pk_mul_f32 v[54:55], v[54:55], v[244:245] op_sel_hi:[1,0]
	v_pk_mul_f32 v[52:53], v[160:161], v[52:53]
	v_pk_mul_f32 v[54:55], v[162:163], v[54:55]
	global_store_dwordx4 v230, v[52:55], s[80:81] offset:512
	v_pk_mul_f32 v[48:49], v[48:49], v[244:245] op_sel_hi:[1,0]
	v_pk_mul_f32 v[50:51], v[50:51], v[244:245] op_sel_hi:[1,0]
	v_pk_mul_f32 v[48:49], v[164:165], v[48:49]
	v_pk_mul_f32 v[50:51], v[166:167], v[50:51]
	global_store_dwordx4 v230, v[48:51], s[80:81] offset:576
	v_add_u32_e32 v230, 0x10000, v230
	s_waitcnt vmcnt(26)
	v_fmamk_f32 v244, v239, 0x3a800000, v198
	v_mul_f32_e32 v140, 0x4b800000, v244
	v_cmp_gt_f32_e32 vcc, s40, v244
	s_nop 1
	v_cndmask_b32_e32 v244, v244, v140, vcc
	v_rsq_f32_e32 v244, v244
	s_nop 0
	v_mul_f32_e32 v140, 0x45800000, v244
	v_cndmask_b32_e32 v244, v244, v140, vcc
	v_pk_mul_f32 v[44:45], v[44:45], v[244:245] op_sel_hi:[1,0]
	v_pk_mul_f32 v[46:47], v[46:47], v[244:245] op_sel_hi:[1,0]
	v_pk_mul_f32 v[44:45], v[152:153], v[44:45]
	v_pk_mul_f32 v[46:47], v[154:155], v[46:47]
	global_store_dwordx4 v230, v[44:47], s[80:81]
	v_pk_mul_f32 v[40:41], v[40:41], v[244:245] op_sel_hi:[1,0]
	v_pk_mul_f32 v[42:43], v[42:43], v[244:245] op_sel_hi:[1,0]
	v_pk_mul_f32 v[40:41], v[156:157], v[40:41]
	v_pk_mul_f32 v[42:43], v[158:159], v[42:43]
	global_store_dwordx4 v230, v[40:43], s[80:81] offset:64
	v_pk_mul_f32 v[36:37], v[36:37], v[244:245] op_sel_hi:[1,0]
	v_pk_mul_f32 v[38:39], v[38:39], v[244:245] op_sel_hi:[1,0]
	v_pk_mul_f32 v[36:37], v[160:161], v[36:37]
	v_pk_mul_f32 v[38:39], v[162:163], v[38:39]
	global_store_dwordx4 v230, v[36:39], s[80:81] offset:512
	v_pk_mul_f32 v[32:33], v[32:33], v[244:245] op_sel_hi:[1,0]
	v_pk_mul_f32 v[34:35], v[34:35], v[244:245] op_sel_hi:[1,0]
	v_pk_mul_f32 v[32:33], v[164:165], v[32:33]
	v_pk_mul_f32 v[34:35], v[166:167], v[34:35]
	global_store_dwordx4 v230, v[32:35], s[80:81] offset:576
	v_add_u32_e32 v230, 0x10000, v230
	s_waitcnt vmcnt(29)
	v_fmamk_f32 v244, v240, 0x3a800000, v198
	v_mul_f32_e32 v140, 0x4b800000, v244
	v_cmp_gt_f32_e32 vcc, s40, v244
	s_nop 1
	v_cndmask_b32_e32 v244, v244, v140, vcc
	v_rsq_f32_e32 v244, v244
	s_nop 0
	v_mul_f32_e32 v140, 0x45800000, v244
	v_cndmask_b32_e32 v244, v244, v140, vcc
	v_pk_mul_f32 v[28:29], v[28:29], v[244:245] op_sel_hi:[1,0]
	v_pk_mul_f32 v[30:31], v[30:31], v[244:245] op_sel_hi:[1,0]
	v_pk_mul_f32 v[28:29], v[152:153], v[28:29]
	v_pk_mul_f32 v[30:31], v[154:155], v[30:31]
	global_store_dwordx4 v230, v[28:31], s[80:81]
	v_pk_mul_f32 v[24:25], v[24:25], v[244:245] op_sel_hi:[1,0]
	v_pk_mul_f32 v[26:27], v[26:27], v[244:245] op_sel_hi:[1,0]
	v_pk_mul_f32 v[24:25], v[156:157], v[24:25]
	v_pk_mul_f32 v[26:27], v[158:159], v[26:27]
	global_store_dwordx4 v230, v[24:27], s[80:81] offset:64
	v_pk_mul_f32 v[20:21], v[20:21], v[244:245] op_sel_hi:[1,0]
	v_pk_mul_f32 v[22:23], v[22:23], v[244:245] op_sel_hi:[1,0]
	v_pk_mul_f32 v[20:21], v[160:161], v[20:21]
	v_pk_mul_f32 v[22:23], v[162:163], v[22:23]
	global_store_dwordx4 v230, v[20:23], s[80:81] offset:512
	v_pk_mul_f32 v[16:17], v[16:17], v[244:245] op_sel_hi:[1,0]
	v_pk_mul_f32 v[18:19], v[18:19], v[244:245] op_sel_hi:[1,0]
	v_pk_mul_f32 v[16:17], v[164:165], v[16:17]
	v_pk_mul_f32 v[18:19], v[166:167], v[18:19]
	global_store_dwordx4 v230, v[16:19], s[80:81] offset:576
	v_add_u32_e32 v230, 0x10000, v230
	s_waitcnt vmcnt(32)
	v_fmamk_f32 v244, v241, 0x3a800000, v198
	v_mul_f32_e32 v140, 0x4b800000, v244
	v_cmp_gt_f32_e32 vcc, s40, v244
	s_nop 1
	v_cndmask_b32_e32 v244, v244, v140, vcc
	v_rsq_f32_e32 v244, v244
	s_nop 0
	v_mul_f32_e32 v140, 0x45800000, v244
	v_cndmask_b32_e32 v244, v244, v140, vcc
	v_pk_mul_f32 v[12:13], v[12:13], v[244:245] op_sel_hi:[1,0]
	v_pk_mul_f32 v[14:15], v[14:15], v[244:245] op_sel_hi:[1,0]
	v_pk_mul_f32 v[12:13], v[152:153], v[12:13]
	v_pk_mul_f32 v[14:15], v[154:155], v[14:15]
	global_store_dwordx4 v230, v[12:15], s[80:81]
	v_pk_mul_f32 v[8:9], v[8:9], v[244:245] op_sel_hi:[1,0]
	v_pk_mul_f32 v[10:11], v[10:11], v[244:245] op_sel_hi:[1,0]
	v_pk_mul_f32 v[8:9], v[156:157], v[8:9]
	v_pk_mul_f32 v[10:11], v[158:159], v[10:11]
	global_store_dwordx4 v230, v[8:11], s[80:81] offset:64
	v_pk_mul_f32 v[4:5], v[4:5], v[244:245] op_sel_hi:[1,0]
	v_pk_mul_f32 v[6:7], v[6:7], v[244:245] op_sel_hi:[1,0]
	v_pk_mul_f32 v[4:5], v[160:161], v[4:5]
	v_pk_mul_f32 v[6:7], v[162:163], v[6:7]
	global_store_dwordx4 v230, v[4:7], s[80:81] offset:512
	v_pk_mul_f32 v[0:1], v[0:1], v[244:245] op_sel_hi:[1,0]
	v_pk_mul_f32 v[2:3], v[2:3], v[244:245] op_sel_hi:[1,0]
	v_pk_mul_f32 v[0:1], v[164:165], v[0:1]
	v_pk_mul_f32 v[2:3], v[166:167], v[2:3]
	global_store_dwordx4 v230, v[0:3], s[80:81] offset:576
	s_and_b64 vcc, exec, s[6:7]
	s_mov_b64 s[6:7], -1
	s_cbranch_vccnz .LBB0_1739
; #define PG8_BAR __builtin_amdgcn_s_barrier()
; template <class Epi, class Sched, bool ALIGN_EPI = false, bool SP2 = false>
; __device__ __forceinline__ void gemm_phase(PG8_LAS unsigned char* lds, const Gemm g, const Sched& S, const Epi& E) {
;     ...
;         cur = nxt; cA = nA; cB = nB; ++ui;
;         if constexpr (ALIGN_EPI) { if (wr == 1) PG8_BAR; }
;     }
	s_andn2_b64 vcc, exec, s[10:11]
	s_cbranch_vccnz .LBB0_1738
	s_barrier
	s_branch .LBB0_1738
